# P7 conv/silu epilogue arithmetic with packed f32 fma/mul/add (same math, f32), plus accumulator zeroing by v_mov_b64
# speedup vs baseline: 1.0527x; 1.0038x over previous
.LBB0_173:
	s_ashr_i32 s29, s28, 31
	s_lshl_b64 s[34:35], s[28:29], 19
	s_add_u32 s34, s33, s34
	s_addc_u32 s35, s48, s35
	s_and_b64 s[36:37], s[30:31], exec
	s_cselect_b32 s29, s35, s1
	s_cselect_b32 s41, s34, s0
	s_ashr_i32 s27, s26, 31
	s_lshl_b64 s[36:37], s[26:27], 19
	s_add_u32 s36, s49, s36
	s_addc_u32 s37, s50, s37
	s_and_b64 s[44:45], s[30:31], exec
	s_cselect_b32 s27, s37, s39
	s_cselect_b32 s43, s36, s38
	s_add_u32 s0, s0, 0x40080
	s_addc_u32 s1, s1, 0
	s_add_u32 s46, s38, 0x100
	v_mov_b32_e32 v0, 0
	s_addc_u32 s47, s39, 0
	s_mov_b32 s63, -2
	v_mov_b32_e32 v1, 0
	v_mov_b64_e32 v[2:3], 0
	v_mov_b64_e32 v[4:5], 0
	v_mov_b64_e32 v[6:7], 0
	v_mov_b64_e32 v[16:17], 0
	v_mov_b64_e32 v[18:19], 0
	v_mov_b64_e32 v[20:21], 0
	v_mov_b64_e32 v[22:23], 0
	v_mov_b64_e32 v[32:33], 0
	v_mov_b64_e32 v[34:35], 0
	v_mov_b64_e32 v[36:37], 0
	v_mov_b64_e32 v[38:39], 0
	v_mov_b64_e32 v[48:49], 0
	v_mov_b64_e32 v[50:51], 0
	v_mov_b64_e32 v[52:53], 0
	v_mov_b64_e32 v[54:55], 0
	v_mov_b64_e32 v[8:9], 0
	v_mov_b64_e32 v[10:11], 0
	v_mov_b64_e32 v[12:13], 0
	v_mov_b64_e32 v[14:15], 0
	v_mov_b64_e32 v[24:25], 0
	v_mov_b64_e32 v[26:27], 0
	v_mov_b64_e32 v[28:29], 0
	v_mov_b64_e32 v[30:31], 0
	v_mov_b64_e32 v[40:41], 0
	v_mov_b64_e32 v[42:43], 0
	v_mov_b64_e32 v[44:45], 0
	v_mov_b64_e32 v[46:47], 0
	v_mov_b64_e32 v[64:65], 0
	v_mov_b64_e32 v[66:67], 0
	v_mov_b64_e32 v[68:69], 0
	v_mov_b64_e32 v[70:71], 0
	v_mov_b64_e32 v[80:81], 0
	v_mov_b64_e32 v[82:83], 0
	v_mov_b64_e32 v[84:85], 0
	v_mov_b64_e32 v[86:87], 0
	v_mov_b64_e32 v[96:97], 0
	v_mov_b64_e32 v[98:99], 0
	v_mov_b64_e32 v[100:101], 0
	v_mov_b64_e32 v[102:103], 0
	v_mov_b64_e32 v[112:113], 0
	v_mov_b64_e32 v[114:115], 0
	v_mov_b64_e32 v[116:117], 0
	v_mov_b64_e32 v[118:119], 0
	v_mov_b64_e32 v[128:129], 0
	v_mov_b64_e32 v[130:131], 0
	v_mov_b64_e32 v[132:133], 0
	v_mov_b64_e32 v[134:135], 0
	v_mov_b64_e32 v[88:89], 0
	v_mov_b64_e32 v[90:91], 0
	v_mov_b64_e32 v[92:93], 0
	v_mov_b64_e32 v[94:95], 0
	v_mov_b64_e32 v[104:105], 0
	v_mov_b64_e32 v[106:107], 0
	v_mov_b64_e32 v[108:109], 0
	v_mov_b64_e32 v[110:111], 0
	v_mov_b64_e32 v[120:121], 0
	v_mov_b64_e32 v[122:123], 0
	v_mov_b64_e32 v[124:125], 0
	v_mov_b64_e32 v[126:127], 0
	v_mov_b64_e32 v[136:137], 0
	v_mov_b64_e32 v[138:139], 0
	v_mov_b64_e32 v[140:141], 0
	v_mov_b64_e32 v[142:143], 0

.LBB0_577:
	s_add_u32 s18, s18, 0x18080
	s_addc_u32 s19, s19, 0
	s_add_u32 s47, s20, 0x100
	v_mov_b32_e32 v0, 0
	s_addc_u32 s48, s21, 0
	s_mov_b32 s49, -2
	v_mov_b32_e32 v1, 0
	v_mov_b64_e32 v[2:3], 0
	v_mov_b64_e32 v[4:5], 0
	v_mov_b64_e32 v[6:7], 0
	v_mov_b64_e32 v[8:9], 0
	v_mov_b64_e32 v[10:11], 0
	v_mov_b64_e32 v[16:17], 0
	v_mov_b64_e32 v[18:19], 0
	v_mov_b64_e32 v[24:25], 0
	v_mov_b64_e32 v[26:27], 0
	v_mov_b64_e32 v[32:33], 0
	v_mov_b64_e32 v[34:35], 0
	v_mov_b64_e32 v[40:41], 0
	v_mov_b64_e32 v[42:43], 0
	v_mov_b64_e32 v[48:49], 0
	v_mov_b64_e32 v[50:51], 0
	v_mov_b64_e32 v[12:13], 0
	v_mov_b64_e32 v[14:15], 0
	v_mov_b64_e32 v[20:21], 0
	v_mov_b64_e32 v[22:23], 0
	v_mov_b64_e32 v[28:29], 0
	v_mov_b64_e32 v[30:31], 0
	v_mov_b64_e32 v[36:37], 0
	v_mov_b64_e32 v[38:39], 0
	v_mov_b64_e32 v[44:45], 0
	v_mov_b64_e32 v[46:47], 0
	v_mov_b64_e32 v[52:53], 0
	v_mov_b64_e32 v[54:55], 0
	v_mov_b64_e32 v[56:57], 0
	v_mov_b64_e32 v[58:59], 0
	v_mov_b64_e32 v[60:61], 0
	v_mov_b64_e32 v[62:63], 0
	v_mov_b64_e32 v[64:65], 0
	v_mov_b64_e32 v[66:67], 0
	v_mov_b64_e32 v[68:69], 0
	v_mov_b64_e32 v[70:71], 0
	v_mov_b64_e32 v[72:73], 0
	v_mov_b64_e32 v[74:75], 0
	v_mov_b64_e32 v[80:81], 0
	v_mov_b64_e32 v[82:83], 0
	v_mov_b64_e32 v[88:89], 0
	v_mov_b64_e32 v[90:91], 0
	v_mov_b64_e32 v[96:97], 0
	v_mov_b64_e32 v[98:99], 0
	v_mov_b64_e32 v[104:105], 0
	v_mov_b64_e32 v[106:107], 0
	v_mov_b64_e32 v[112:113], 0
	v_mov_b64_e32 v[114:115], 0
	v_mov_b64_e32 v[76:77], 0
	v_mov_b64_e32 v[78:79], 0
	v_mov_b64_e32 v[84:85], 0
	v_mov_b64_e32 v[86:87], 0
	v_mov_b64_e32 v[92:93], 0
	v_mov_b64_e32 v[94:95], 0
	v_mov_b64_e32 v[100:101], 0
	v_mov_b64_e32 v[102:103], 0
	v_mov_b64_e32 v[108:109], 0
	v_mov_b64_e32 v[110:111], 0
	v_mov_b64_e32 v[116:117], 0
	v_mov_b64_e32 v[118:119], 0
	v_mov_b64_e32 v[120:121], 0
	v_mov_b64_e32 v[122:123], 0
	v_mov_b64_e32 v[124:125], 0
	v_mov_b64_e32 v[126:127], 0

.LBB0_607:
	s_ashr_i32 s23, s22, 31
	s_lshl_b64 s[26:27], s[22:23], 17
	s_add_u32 s26, s50, s26
	s_addc_u32 s27, s51, s27
	s_and_b64 s[28:29], s[24:25], exec
	s_cselect_b32 s23, s27, s37
	s_cselect_b32 s31, s26, s36
	s_ashr_i32 s21, s20, 31
	s_lshl_b64 s[28:29], s[20:21], 17
	s_add_u32 s28, s52, s28
	s_addc_u32 s29, s53, s29
	s_and_b64 s[40:41], s[24:25], exec
	v_mov_b32_e32 v0, 0
	s_cselect_b32 s21, s29, s1
	s_cselect_b32 s35, s28, s0
	s_mov_b32 s44, 0
	s_mov_b64 s[40:41], -1
	v_mov_b32_e32 v1, 0
	v_mov_b64_e32 v[2:3], 0
	v_mov_b64_e32 v[4:5], 0
	v_mov_b64_e32 v[6:7], 0
	v_mov_b64_e32 v[16:17], 0
	v_mov_b64_e32 v[18:19], 0
	v_mov_b64_e32 v[20:21], 0
	v_mov_b64_e32 v[22:23], 0
	v_mov_b64_e32 v[32:33], 0
	v_mov_b64_e32 v[34:35], 0
	v_mov_b64_e32 v[36:37], 0
	v_mov_b64_e32 v[38:39], 0
	v_mov_b64_e32 v[48:49], 0
	v_mov_b64_e32 v[50:51], 0
	v_mov_b64_e32 v[52:53], 0
	v_mov_b64_e32 v[54:55], 0
	v_mov_b64_e32 v[8:9], 0
	v_mov_b64_e32 v[10:11], 0
	v_mov_b64_e32 v[12:13], 0
	v_mov_b64_e32 v[14:15], 0
	v_mov_b64_e32 v[24:25], 0
	v_mov_b64_e32 v[26:27], 0
	v_mov_b64_e32 v[28:29], 0
	v_mov_b64_e32 v[30:31], 0
	v_mov_b64_e32 v[40:41], 0
	v_mov_b64_e32 v[42:43], 0
	v_mov_b64_e32 v[44:45], 0
	v_mov_b64_e32 v[46:47], 0
	v_mov_b64_e32 v[56:57], 0
	v_mov_b64_e32 v[58:59], 0
	v_mov_b64_e32 v[60:61], 0
	v_mov_b64_e32 v[62:63], 0
	v_mov_b64_e32 v[64:65], 0
	v_mov_b64_e32 v[66:67], 0
	v_mov_b64_e32 v[68:69], 0
	v_mov_b64_e32 v[70:71], 0
	v_mov_b64_e32 v[80:81], 0
	v_mov_b64_e32 v[82:83], 0
	v_mov_b64_e32 v[84:85], 0
	v_mov_b64_e32 v[86:87], 0
	v_mov_b64_e32 v[96:97], 0
	v_mov_b64_e32 v[98:99], 0
	v_mov_b64_e32 v[100:101], 0
	v_mov_b64_e32 v[102:103], 0
	v_mov_b64_e32 v[112:113], 0
	v_mov_b64_e32 v[114:115], 0
	v_mov_b64_e32 v[116:117], 0
	v_mov_b64_e32 v[118:119], 0
	v_mov_b64_e32 v[72:73], 0
	v_mov_b64_e32 v[74:75], 0
	v_mov_b64_e32 v[76:77], 0
	v_mov_b64_e32 v[78:79], 0
	v_mov_b64_e32 v[88:89], 0
	v_mov_b64_e32 v[90:91], 0
	v_mov_b64_e32 v[92:93], 0
	v_mov_b64_e32 v[94:95], 0
	v_mov_b64_e32 v[104:105], 0
	v_mov_b64_e32 v[106:107], 0
	v_mov_b64_e32 v[108:109], 0
	v_mov_b64_e32 v[110:111], 0
	v_mov_b64_e32 v[120:121], 0
	v_mov_b64_e32 v[122:123], 0
	v_mov_b64_e32 v[124:125], 0
	v_mov_b64_e32 v[126:127], 0

.LBB0_973:
	s_add_i32 m0, s29, 0x18000
	v_lshl_add_u64 v[0:1], v[0:1], 0, s[24:25]
	s_and_b32 s11, s65, 3
	s_lshl_b32 s75, s66, 6
	s_lshl_b32 s34, s66, 13
	s_waitcnt vmcnt(2)
	s_barrier
	global_load_lds_dwordx4 v[0:1], off
	v_lshl_add_u64 v[0:1], v[2:3], 0, s[24:25]
	s_add_i32 m0, s29, 0x1a000
	s_add_i32 s78, s29, 0x8000
	s_add_i32 s79, s29, 0xa000
	v_bitop3_b32 v8, v186, s34, v187 bitop3:0xde
	global_load_lds_dwordx4 v[0:1], off
	v_lshl_add_u64 v[0:1], v[6:7], 0, s[24:25]
	s_mov_b32 m0, s78
	s_add_u32 s34, s48, 0x40080
	global_load_lds_dwordx4 v[0:1], off
	v_lshl_add_u64 v[0:1], v[4:5], 0, s[24:25]
	s_mov_b32 m0, s79
	s_addc_u32 s35, s49, 0
	global_load_lds_dwordx4 v[0:1], off
	s_add_i32 m0, s29, 0x1c000
	v_lshl_add_u64 v[0:1], s[34:35], 0, v[164:165]
	global_load_lds_dwordx4 v[0:1], off
	v_lshl_add_u64 v[0:1], s[34:35], 0, v[168:169]
	s_add_i32 m0, s29, 0x1e000
	v_or_b32_e32 v181, s75, v161
	global_load_lds_dwordx4 v[0:1], off
	s_waitcnt vmcnt(6)
	v_mov_b32_e32 v0, 0
	v_lshl_or_b32 v132, s11, 12, v183
	s_mov_b32 s80, 0
	v_add_u32_e32 v133, 0, v8
	v_mov_b32_e32 v1, 0
	v_mov_b64_e32 v[2:3], 0
	v_mov_b64_e32 v[4:5], 0
	v_mov_b64_e32 v[6:7], 0
	v_mov_b64_e32 v[16:17], 0
	v_mov_b64_e32 v[18:19], 0
	v_mov_b64_e32 v[20:21], 0
	v_mov_b64_e32 v[22:23], 0
	v_mov_b64_e32 v[32:33], 0
	v_mov_b64_e32 v[34:35], 0
	v_mov_b64_e32 v[36:37], 0
	v_mov_b64_e32 v[38:39], 0
	v_mov_b64_e32 v[48:49], 0
	v_mov_b64_e32 v[50:51], 0
	v_mov_b64_e32 v[52:53], 0
	v_mov_b64_e32 v[54:55], 0
	v_mov_b64_e32 v[8:9], 0
	v_mov_b64_e32 v[10:11], 0
	v_mov_b64_e32 v[12:13], 0
	v_mov_b64_e32 v[14:15], 0
	v_mov_b64_e32 v[24:25], 0
	v_mov_b64_e32 v[26:27], 0
	v_mov_b64_e32 v[28:29], 0
	v_mov_b64_e32 v[30:31], 0
	v_mov_b64_e32 v[40:41], 0
	v_mov_b64_e32 v[42:43], 0
	v_mov_b64_e32 v[44:45], 0
	v_mov_b64_e32 v[46:47], 0
	v_mov_b64_e32 v[56:57], 0
	v_mov_b64_e32 v[58:59], 0
	v_mov_b64_e32 v[60:61], 0
	v_mov_b64_e32 v[62:63], 0
	v_mov_b64_e32 v[64:65], 0
	v_mov_b64_e32 v[66:67], 0
	v_mov_b64_e32 v[72:73], 0
	v_mov_b64_e32 v[74:75], 0
	v_mov_b64_e32 v[84:85], 0
	v_mov_b64_e32 v[86:87], 0
	v_mov_b64_e32 v[92:93], 0
	v_mov_b64_e32 v[94:95], 0
	v_mov_b64_e32 v[68:69], 0
	v_mov_b64_e32 v[70:71], 0
	v_mov_b64_e32 v[76:77], 0
	v_mov_b64_e32 v[78:79], 0
	v_mov_b64_e32 v[80:81], 0
	v_mov_b64_e32 v[82:83], 0
	v_mov_b64_e32 v[88:89], 0
	v_mov_b64_e32 v[90:91], 0
	v_mov_b64_e32 v[116:117], 0
	v_mov_b64_e32 v[118:119], 0
	v_mov_b64_e32 v[124:125], 0
	v_mov_b64_e32 v[126:127], 0
	v_mov_b64_e32 v[112:113], 0
	v_mov_b64_e32 v[114:115], 0
	v_mov_b64_e32 v[120:121], 0
	v_mov_b64_e32 v[122:123], 0
	v_mov_b64_e32 v[104:105], 0
	v_mov_b64_e32 v[106:107], 0
	v_mov_b64_e32 v[108:109], 0
	v_mov_b64_e32 v[110:111], 0
	v_mov_b64_e32 v[96:97], 0
	v_mov_b64_e32 v[98:99], 0
	v_mov_b64_e32 v[100:101], 0
	v_mov_b64_e32 v[102:103], 0
	s_barrier
	s_add_i32 s81, s80, 1
	s_cmp_ge_i32 s81, s68
	s_mov_b64 s[42:43], 0
	s_cbranch_scc0 .LBB0_975

.LBB0_982:
	s_add_u32 s48, s30, s42
	s_addc_u32 s49, s31, s43
	s_add_u32 s48, s48, 0x100
	s_addc_u32 s49, s49, 0
	s_add_u32 s87, s82, s42
	s_addc_u32 s88, s83, s43
	s_add_i32 s89, 0, 0x10000
	s_cmpk_eq_i32 s42, 0x700
	s_cselect_b32 s51, s37, s49
	s_cselect_b32 s50, s84, s48
	s_cselect_b32 s49, s35, s88
	s_cselect_b32 s48, s85, s87
	s_add_i32 s87, 0, 0x14000
	v_add_u32_e32 v146, s89, v132
	v_add_u32_e32 v158, s87, v132
	ds_read_b128 v[134:137], v146
	ds_read_b128 v[138:141], v146 offset:1024
	ds_read_b128 v[142:145], v146 offset:2048
	ds_read_b128 v[146:149], v146 offset:3072
	ds_read_b128 v[150:153], v158
	ds_read_b128 v[154:157], v158 offset:1024
	ds_read_b128 v[194:197], v158 offset:2048
	ds_read_b128 v[198:201], v158 offset:3072
	v_lshl_add_u64 v[158:159], v[128:129], 0, s[42:43]
	s_add_i32 m0, s29, 0xc000
	ds_read_b128 v[202:205], v133
	ds_read_b128 v[206:209], v133 offset:1024
	ds_read_b128 v[210:213], v133 offset:2048
	ds_read_b128 v[214:217], v133 offset:3072
	ds_read_b128 v[218:221], v133 offset:4096
	ds_read_b128 v[222:225], v133 offset:5120
	ds_read_b128 v[226:229], v133 offset:6144
	ds_read_b128 v[230:233], v133 offset:7168
	global_load_lds_dwordx4 v[158:159], off
	v_lshl_add_u64 v[158:159], v[130:131], 0, s[42:43]
	s_add_i32 m0, s29, 0xe000
	s_nop 0
	global_load_lds_dwordx4 v[158:159], off
	s_waitcnt vmcnt(8)
	s_waitcnt lgkmcnt(0)
	s_barrier
	s_setprio 1
	s_waitcnt lgkmcnt(0)
	v_mfma_f32_16x16x32_bf16 v[100:103], v[134:137], v[202:205], v[100:103]
	v_mfma_f32_16x16x32_bf16 v[96:99], v[142:145], v[202:205], v[96:99]
	v_mfma_f32_16x16x32_bf16 v[108:111], v[134:137], v[210:213], v[108:111]
	v_mfma_f32_16x16x32_bf16 v[104:107], v[142:145], v[210:213], v[104:107]
	v_mfma_f32_16x16x32_bf16 v[120:123], v[134:137], v[218:221], v[120:123]
	v_mfma_f32_16x16x32_bf16 v[112:115], v[142:145], v[218:221], v[112:115]
	v_mfma_f32_16x16x32_bf16 v[124:127], v[134:137], v[226:229], v[124:127]
	v_mfma_f32_16x16x32_bf16 v[116:119], v[142:145], v[226:229], v[116:119]
	v_mfma_f32_16x16x32_bf16 v[100:103], v[138:141], v[206:209], v[100:103]
	v_mfma_f32_16x16x32_bf16 v[96:99], v[146:149], v[206:209], v[96:99]
	v_mfma_f32_16x16x32_bf16 v[108:111], v[138:141], v[214:217], v[108:111]
	v_mfma_f32_16x16x32_bf16 v[104:107], v[146:149], v[214:217], v[104:107]
	v_mfma_f32_16x16x32_bf16 v[120:123], v[138:141], v[222:225], v[120:123]
	v_mfma_f32_16x16x32_bf16 v[112:115], v[146:149], v[222:225], v[112:115]
	v_mfma_f32_16x16x32_bf16 v[124:127], v[138:141], v[230:233], v[124:127]
	v_mfma_f32_16x16x32_bf16 v[116:119], v[146:149], v[230:233], v[116:119]
	s_setprio 0
	s_setprio 1
	v_mfma_f32_16x16x32_bf16 v[88:91], v[150:153], v[202:205], v[88:91]
	v_mfma_f32_16x16x32_bf16 v[80:83], v[194:197], v[202:205], v[80:83]
	v_mfma_f32_16x16x32_bf16 v[76:79], v[150:153], v[210:213], v[76:79]
	v_mfma_f32_16x16x32_bf16 v[68:71], v[194:197], v[210:213], v[68:71]
	v_mfma_f32_16x16x32_bf16 v[92:95], v[150:153], v[218:221], v[92:95]
	v_mfma_f32_16x16x32_bf16 v[84:87], v[194:197], v[218:221], v[84:87]
	v_mfma_f32_16x16x32_bf16 v[72:75], v[150:153], v[226:229], v[72:75]
	v_mfma_f32_16x16x32_bf16 v[64:67], v[194:197], v[226:229], v[64:67]
	v_mfma_f32_16x16x32_bf16 v[88:91], v[154:157], v[206:209], v[88:91]
	v_mfma_f32_16x16x32_bf16 v[80:83], v[198:201], v[206:209], v[80:83]
	v_mfma_f32_16x16x32_bf16 v[76:79], v[154:157], v[214:217], v[76:79]
	v_mfma_f32_16x16x32_bf16 v[68:71], v[198:201], v[214:217], v[68:71]
	v_mfma_f32_16x16x32_bf16 v[92:95], v[154:157], v[222:225], v[92:95]
	v_mfma_f32_16x16x32_bf16 v[84:87], v[198:201], v[222:225], v[84:87]
	v_mfma_f32_16x16x32_bf16 v[72:75], v[154:157], v[230:233], v[72:75]
	v_mfma_f32_16x16x32_bf16 v[64:67], v[198:201], v[230:233], v[64:67]
	s_setprio 0
	s_barrier
	s_add_i32 s88, s89, s73
	v_lshl_add_u64 v[158:159], s[48:49], 0, v[164:165]
	s_mov_b32 m0, s88
	ds_read_b128 v[202:205], v133 offset:16384
	ds_read_b128 v[206:209], v133 offset:17408
	ds_read_b128 v[210:213], v133 offset:18432
	ds_read_b128 v[214:217], v133 offset:19456
	ds_read_b128 v[218:221], v133 offset:20480
	ds_read_b128 v[222:225], v133 offset:21504
	ds_read_b128 v[226:229], v133 offset:22528
	ds_read_b128 v[230:233], v133 offset:23552
	global_load_lds_dwordx4 v[158:159], off
	s_add_i32 m0, s88, 0x2000
	s_add_u32 s88, s48, 0x40000
	v_lshl_add_u64 v[178:179], s[48:49], 0, v[168:169]
	s_addc_u32 s89, s49, 0
	s_add_i32 s87, s87, s73
	global_load_lds_dwordx4 v[178:179], off
	v_lshl_add_u64 v[234:235], s[88:89], 0, v[164:165]
	s_mov_b32 m0, s87
	v_lshl_add_u64 v[236:237], s[50:51], 0, v[166:167]
	global_load_lds_dwordx4 v[234:235], off
	v_lshl_add_u64 v[234:235], s[88:89], 0, v[168:169]
	s_add_i32 m0, s87, 0x2000
	s_nop 0
	global_load_lds_dwordx4 v[234:235], off
	v_lshl_add_u64 v[234:235], s[50:51], 0, v[162:163]
	s_mov_b32 m0, s29
	s_nop 0
	global_load_lds_dwordx4 v[234:235], off
	s_mov_b32 m0, s74
	s_nop 0
	global_load_lds_dwordx4 v[236:237], off
	s_waitcnt vmcnt(8)
	s_waitcnt lgkmcnt(0)
	s_barrier
	s_setprio 1
	s_waitcnt lgkmcnt(0)
	v_mfma_f32_16x16x32_bf16 v[60:63], v[134:137], v[202:205], v[60:63]
	v_mfma_f32_16x16x32_bf16 v[56:59], v[142:145], v[202:205], v[56:59]
	v_mfma_f32_16x16x32_bf16 v[44:47], v[134:137], v[210:213], v[44:47]
	v_mfma_f32_16x16x32_bf16 v[40:43], v[142:145], v[210:213], v[40:43]
	v_mfma_f32_16x16x32_bf16 v[28:31], v[134:137], v[218:221], v[28:31]
	v_mfma_f32_16x16x32_bf16 v[24:27], v[142:145], v[218:221], v[24:27]
	v_mfma_f32_16x16x32_bf16 v[12:15], v[134:137], v[226:229], v[12:15]
	v_mfma_f32_16x16x32_bf16 v[8:11], v[142:145], v[226:229], v[8:11]
	v_mfma_f32_16x16x32_bf16 v[60:63], v[138:141], v[206:209], v[60:63]
	v_mfma_f32_16x16x32_bf16 v[56:59], v[146:149], v[206:209], v[56:59]
	v_mfma_f32_16x16x32_bf16 v[44:47], v[138:141], v[214:217], v[44:47]
	v_mfma_f32_16x16x32_bf16 v[40:43], v[146:149], v[214:217], v[40:43]
	v_mfma_f32_16x16x32_bf16 v[28:31], v[138:141], v[222:225], v[28:31]
	v_mfma_f32_16x16x32_bf16 v[24:27], v[146:149], v[222:225], v[24:27]
	v_mfma_f32_16x16x32_bf16 v[12:15], v[138:141], v[230:233], v[12:15]
	v_mfma_f32_16x16x32_bf16 v[8:11], v[146:149], v[230:233], v[8:11]
	s_setprio 0
	s_setprio 1
	v_mfma_f32_16x16x32_bf16 v[52:55], v[150:153], v[202:205], v[52:55]
	v_mfma_f32_16x16x32_bf16 v[48:51], v[194:197], v[202:205], v[48:51]
	v_mfma_f32_16x16x32_bf16 v[36:39], v[150:153], v[210:213], v[36:39]
	v_mfma_f32_16x16x32_bf16 v[32:35], v[194:197], v[210:213], v[32:35]
	v_mfma_f32_16x16x32_bf16 v[20:23], v[150:153], v[218:221], v[20:23]
	v_mfma_f32_16x16x32_bf16 v[16:19], v[194:197], v[218:221], v[16:19]
	v_mfma_f32_16x16x32_bf16 v[4:7], v[150:153], v[226:229], v[4:7]
	v_mfma_f32_16x16x32_bf16 v[0:3], v[194:197], v[226:229], v[0:3]
	v_mfma_f32_16x16x32_bf16 v[52:55], v[154:157], v[206:209], v[52:55]
	v_mfma_f32_16x16x32_bf16 v[48:51], v[198:201], v[206:209], v[48:51]
	v_mfma_f32_16x16x32_bf16 v[36:39], v[154:157], v[214:217], v[36:39]
	v_mfma_f32_16x16x32_bf16 v[32:35], v[198:201], v[214:217], v[32:35]
	v_mfma_f32_16x16x32_bf16 v[20:23], v[154:157], v[222:225], v[20:23]
	v_mfma_f32_16x16x32_bf16 v[16:19], v[198:201], v[222:225], v[16:19]
	v_mfma_f32_16x16x32_bf16 v[4:7], v[154:157], v[230:233], v[4:7]
	v_mfma_f32_16x16x32_bf16 v[0:3], v[198:201], v[230:233], v[0:3]
	s_setprio 0
	s_barrier
	s_add_i32 s87, 0, 0x18000
	s_add_i32 s88, 0, 0x1c000
	v_add_u32_e32 v146, s87, v132
	v_add_u32_e32 v170, s88, v132
	ds_read_b128 v[134:137], v146
	ds_read_b128 v[138:141], v146 offset:1024
	ds_read_b128 v[142:145], v146 offset:2048
	ds_read_b128 v[146:149], v146 offset:3072
	ds_read_b128 v[150:153], v170
	ds_read_b128 v[154:157], v170 offset:1024
	ds_read_b128 v[194:197], v170 offset:2048
	ds_read_b128 v[198:201], v170 offset:3072
	s_add_u32 s50, s50, 0x40000
	s_addc_u32 s51, s51, 0
	s_mov_b32 m0, s76
	v_lshl_add_u64 v[238:239], s[50:51], 0, v[162:163]
	ds_read_b128 v[202:205], v133 offset:32768
	ds_read_b128 v[206:209], v133 offset:33792
	ds_read_b128 v[210:213], v133 offset:34816
	ds_read_b128 v[214:217], v133 offset:35840
	ds_read_b128 v[218:221], v133 offset:36864
	ds_read_b128 v[222:225], v133 offset:37888
	ds_read_b128 v[226:229], v133 offset:38912
	ds_read_b128 v[230:233], v133 offset:39936
	global_load_lds_dwordx4 v[238:239], off
	v_lshl_add_u64 v[238:239], s[50:51], 0, v[166:167]
	s_mov_b32 m0, s77
	s_nop 0
	global_load_lds_dwordx4 v[238:239], off
	s_waitcnt vmcnt(8)
	s_waitcnt lgkmcnt(0)
	s_barrier
	s_setprio 1
	s_waitcnt lgkmcnt(0)
	v_mfma_f32_16x16x32_bf16 v[100:103], v[134:137], v[202:205], v[100:103]
	v_mfma_f32_16x16x32_bf16 v[96:99], v[142:145], v[202:205], v[96:99]
	v_mfma_f32_16x16x32_bf16 v[108:111], v[134:137], v[210:213], v[108:111]
	v_mfma_f32_16x16x32_bf16 v[104:107], v[142:145], v[210:213], v[104:107]
	v_mfma_f32_16x16x32_bf16 v[120:123], v[134:137], v[218:221], v[120:123]
	v_mfma_f32_16x16x32_bf16 v[112:115], v[142:145], v[218:221], v[112:115]
	v_mfma_f32_16x16x32_bf16 v[124:127], v[134:137], v[226:229], v[124:127]
	v_mfma_f32_16x16x32_bf16 v[116:119], v[142:145], v[226:229], v[116:119]
	v_mfma_f32_16x16x32_bf16 v[100:103], v[138:141], v[206:209], v[100:103]
	v_mfma_f32_16x16x32_bf16 v[96:99], v[146:149], v[206:209], v[96:99]
	v_mfma_f32_16x16x32_bf16 v[108:111], v[138:141], v[214:217], v[108:111]
	v_mfma_f32_16x16x32_bf16 v[104:107], v[146:149], v[214:217], v[104:107]
	v_mfma_f32_16x16x32_bf16 v[120:123], v[138:141], v[222:225], v[120:123]
	v_mfma_f32_16x16x32_bf16 v[112:115], v[146:149], v[222:225], v[112:115]
	v_mfma_f32_16x16x32_bf16 v[124:127], v[138:141], v[230:233], v[124:127]
	v_mfma_f32_16x16x32_bf16 v[116:119], v[146:149], v[230:233], v[116:119]
	s_setprio 0
	s_setprio 1
	v_mfma_f32_16x16x32_bf16 v[88:91], v[150:153], v[202:205], v[88:91]
	v_mfma_f32_16x16x32_bf16 v[80:83], v[194:197], v[202:205], v[80:83]
	v_mfma_f32_16x16x32_bf16 v[76:79], v[150:153], v[210:213], v[76:79]
	v_mfma_f32_16x16x32_bf16 v[68:71], v[194:197], v[210:213], v[68:71]
	v_mfma_f32_16x16x32_bf16 v[92:95], v[150:153], v[218:221], v[92:95]
	v_mfma_f32_16x16x32_bf16 v[84:87], v[194:197], v[218:221], v[84:87]
	v_mfma_f32_16x16x32_bf16 v[72:75], v[150:153], v[226:229], v[72:75]
	v_mfma_f32_16x16x32_bf16 v[64:67], v[194:197], v[226:229], v[64:67]
	v_mfma_f32_16x16x32_bf16 v[88:91], v[154:157], v[206:209], v[88:91]
	v_mfma_f32_16x16x32_bf16 v[80:83], v[198:201], v[206:209], v[80:83]
	v_mfma_f32_16x16x32_bf16 v[76:79], v[154:157], v[214:217], v[76:79]
	v_mfma_f32_16x16x32_bf16 v[68:71], v[198:201], v[214:217], v[68:71]
	v_mfma_f32_16x16x32_bf16 v[92:95], v[154:157], v[222:225], v[92:95]
	v_mfma_f32_16x16x32_bf16 v[84:87], v[198:201], v[222:225], v[84:87]
	v_mfma_f32_16x16x32_bf16 v[72:75], v[154:157], v[230:233], v[72:75]
	v_mfma_f32_16x16x32_bf16 v[64:67], v[198:201], v[230:233], v[64:67]
	s_setprio 0
	s_barrier
	s_add_i32 s50, s87, s73
	v_lshl_add_u64 v[158:159], v[158:159], 0, s[24:25]
	s_mov_b32 m0, s50
	ds_read_b128 v[202:205], v133 offset:49152
	ds_read_b128 v[206:209], v133 offset:50176
	ds_read_b128 v[210:213], v133 offset:51200
	ds_read_b128 v[214:217], v133 offset:52224
	ds_read_b128 v[218:221], v133 offset:53248
	ds_read_b128 v[222:225], v133 offset:54272
	ds_read_b128 v[226:229], v133 offset:55296
	ds_read_b128 v[230:233], v133 offset:56320
	global_load_lds_dwordx4 v[158:159], off
	s_add_i32 m0, s50, 0x2000
	s_add_u32 s48, s48, 0x40080
	v_lshl_add_u64 v[158:159], v[178:179], 0, s[24:25]
	s_addc_u32 s49, s49, 0
	s_add_i32 s50, s88, s73
	global_load_lds_dwordx4 v[158:159], off
	v_lshl_add_u64 v[158:159], s[48:49], 0, v[164:165]
	s_mov_b32 m0, s50
	s_nop 0
	global_load_lds_dwordx4 v[158:159], off
	v_lshl_add_u64 v[158:159], s[48:49], 0, v[168:169]
	s_add_i32 m0, s50, 0x2000
	s_nop 0
	global_load_lds_dwordx4 v[158:159], off
	v_lshl_add_u64 v[158:159], v[234:235], 0, s[24:25]
	s_mov_b32 m0, s78
	s_nop 0
	global_load_lds_dwordx4 v[158:159], off
	v_lshl_add_u64 v[158:159], v[236:237], 0, s[24:25]
	s_mov_b32 m0, s79
	s_nop 0
	global_load_lds_dwordx4 v[158:159], off
	s_waitcnt vmcnt(8)
	s_waitcnt lgkmcnt(0)
	s_barrier
	s_setprio 1
	s_waitcnt lgkmcnt(0)
	v_mfma_f32_16x16x32_bf16 v[60:63], v[134:137], v[202:205], v[60:63]
	v_mfma_f32_16x16x32_bf16 v[56:59], v[142:145], v[202:205], v[56:59]
	v_mfma_f32_16x16x32_bf16 v[44:47], v[134:137], v[210:213], v[44:47]
	v_mfma_f32_16x16x32_bf16 v[40:43], v[142:145], v[210:213], v[40:43]
	v_mfma_f32_16x16x32_bf16 v[28:31], v[134:137], v[218:221], v[28:31]
	v_mfma_f32_16x16x32_bf16 v[24:27], v[142:145], v[218:221], v[24:27]
	v_mfma_f32_16x16x32_bf16 v[12:15], v[134:137], v[226:229], v[12:15]
	v_mfma_f32_16x16x32_bf16 v[8:11], v[142:145], v[226:229], v[8:11]
	v_mfma_f32_16x16x32_bf16 v[60:63], v[138:141], v[206:209], v[60:63]
	v_mfma_f32_16x16x32_bf16 v[56:59], v[146:149], v[206:209], v[56:59]
	v_mfma_f32_16x16x32_bf16 v[44:47], v[138:141], v[214:217], v[44:47]
	v_mfma_f32_16x16x32_bf16 v[40:43], v[146:149], v[214:217], v[40:43]
	v_mfma_f32_16x16x32_bf16 v[28:31], v[138:141], v[222:225], v[28:31]
	v_mfma_f32_16x16x32_bf16 v[24:27], v[146:149], v[222:225], v[24:27]
	v_mfma_f32_16x16x32_bf16 v[12:15], v[138:141], v[230:233], v[12:15]
	v_mfma_f32_16x16x32_bf16 v[8:11], v[146:149], v[230:233], v[8:11]
	s_setprio 0
	s_setprio 1
	v_mfma_f32_16x16x32_bf16 v[52:55], v[150:153], v[202:205], v[52:55]
	v_mfma_f32_16x16x32_bf16 v[48:51], v[194:197], v[202:205], v[48:51]
	v_mfma_f32_16x16x32_bf16 v[36:39], v[150:153], v[210:213], v[36:39]
	v_mfma_f32_16x16x32_bf16 v[32:35], v[194:197], v[210:213], v[32:35]
	v_mfma_f32_16x16x32_bf16 v[20:23], v[150:153], v[218:221], v[20:23]
	v_mfma_f32_16x16x32_bf16 v[16:19], v[194:197], v[218:221], v[16:19]
	v_mfma_f32_16x16x32_bf16 v[4:7], v[150:153], v[226:229], v[4:7]
	v_mfma_f32_16x16x32_bf16 v[0:3], v[194:197], v[226:229], v[0:3]
	v_mfma_f32_16x16x32_bf16 v[52:55], v[154:157], v[206:209], v[52:55]
	v_mfma_f32_16x16x32_bf16 v[48:51], v[198:201], v[206:209], v[48:51]
	v_mfma_f32_16x16x32_bf16 v[36:39], v[154:157], v[214:217], v[36:39]
	v_mfma_f32_16x16x32_bf16 v[32:35], v[198:201], v[214:217], v[32:35]
	v_mfma_f32_16x16x32_bf16 v[20:23], v[154:157], v[222:225], v[20:23]
	v_mfma_f32_16x16x32_bf16 v[16:19], v[198:201], v[222:225], v[16:19]
	v_mfma_f32_16x16x32_bf16 v[4:7], v[154:157], v[230:233], v[4:7]
	v_mfma_f32_16x16x32_bf16 v[0:3], v[198:201], v[230:233], v[0:3]
	s_setprio 0
	s_barrier
	s_add_i32 s86, s86, 2
	s_add_u32 s42, s42, 0x100
	s_addc_u32 s43, s43, 0
	s_cmp_gt_u32 s86, 13
	s_cbranch_scc0 .LBB0_982
	s_add_u32 s42, s82, 0xffffff00
	s_addc_u32 s43, s83, -1
	s_andn2_b64 vcc, exec, s[44:45]
	s_cbranch_vccnz .LBB0_985
	v_mov_b32_e32 v0, 0
	s_mov_b32 s28, s34
	s_mov_b32 s10, s36
	s_mov_b64 s[30:31], s[46:47]
	s_mov_b32 s80, s81
	v_mov_b32_e32 v1, 0
	v_mov_b64_e32 v[2:3], 0
	v_mov_b64_e32 v[4:5], 0
	v_mov_b64_e32 v[6:7], 0
	v_mov_b64_e32 v[16:17], 0
	v_mov_b64_e32 v[18:19], 0
	v_mov_b64_e32 v[20:21], 0
	v_mov_b64_e32 v[22:23], 0
	v_mov_b64_e32 v[32:33], 0
	v_mov_b64_e32 v[34:35], 0
	v_mov_b64_e32 v[36:37], 0
	v_mov_b64_e32 v[38:39], 0
	v_mov_b64_e32 v[48:49], 0
	v_mov_b64_e32 v[50:51], 0
	v_mov_b64_e32 v[52:53], 0
	v_mov_b64_e32 v[54:55], 0
	v_mov_b64_e32 v[8:9], 0
	v_mov_b64_e32 v[10:11], 0
	v_mov_b64_e32 v[12:13], 0
	v_mov_b64_e32 v[14:15], 0
	v_mov_b64_e32 v[24:25], 0
	v_mov_b64_e32 v[26:27], 0
	v_mov_b64_e32 v[28:29], 0
	v_mov_b64_e32 v[30:31], 0
	v_mov_b64_e32 v[40:41], 0
	v_mov_b64_e32 v[42:43], 0
	v_mov_b64_e32 v[44:45], 0
	v_mov_b64_e32 v[46:47], 0
	v_mov_b64_e32 v[56:57], 0
	v_mov_b64_e32 v[58:59], 0
	v_mov_b64_e32 v[60:61], 0
	v_mov_b64_e32 v[62:63], 0
	v_mov_b64_e32 v[64:65], 0
	v_mov_b64_e32 v[66:67], 0
	v_mov_b64_e32 v[72:73], 0
	v_mov_b64_e32 v[74:75], 0
	v_mov_b64_e32 v[84:85], 0
	v_mov_b64_e32 v[86:87], 0
	v_mov_b64_e32 v[92:93], 0
	v_mov_b64_e32 v[94:95], 0
	v_mov_b64_e32 v[68:69], 0
	v_mov_b64_e32 v[70:71], 0
	v_mov_b64_e32 v[76:77], 0
	v_mov_b64_e32 v[78:79], 0
	v_mov_b64_e32 v[80:81], 0
	v_mov_b64_e32 v[82:83], 0
	v_mov_b64_e32 v[88:89], 0
	v_mov_b64_e32 v[90:91], 0
	v_mov_b64_e32 v[116:117], 0
	v_mov_b64_e32 v[118:119], 0
	v_mov_b64_e32 v[124:125], 0
	v_mov_b64_e32 v[126:127], 0
	v_mov_b64_e32 v[112:113], 0
	v_mov_b64_e32 v[114:115], 0
	v_mov_b64_e32 v[120:121], 0
	v_mov_b64_e32 v[122:123], 0
	v_mov_b64_e32 v[104:105], 0
	v_mov_b64_e32 v[106:107], 0
	v_mov_b64_e32 v[108:109], 0
	v_mov_b64_e32 v[110:111], 0
	v_mov_b64_e32 v[96:97], 0
	v_mov_b64_e32 v[98:99], 0
	v_mov_b64_e32 v[100:101], 0
	v_mov_b64_e32 v[102:103], 0
	s_andn2_b64 vcc, exec, s[38:39]
	s_cbranch_vccnz .LBB0_986
	s_branch .LBB0_987

.LBB0_1100:
	s_ashr_i32 s37, s36, 31
	s_lshl_b64 s[40:41], s[36:37], 19
	s_add_u32 s40, s55, s40
	s_addc_u32 s41, s56, s41
	s_and_b64 s[42:43], s[38:39], exec
	s_cselect_b32 s37, s41, s49
	s_cselect_b32 s45, s40, s48
	s_ashr_i32 s35, s34, 31
	s_lshl_b64 s[42:43], s[34:35], 19
	s_add_u32 s42, s57, s42
	s_addc_u32 s43, s58, s43
	s_and_b64 s[52:53], s[38:39], exec
	s_cselect_b32 s35, s43, s51
	s_cselect_b32 s47, s42, s50
	s_add_u32 s48, s48, 0x40080
	s_addc_u32 s49, s49, 0
	s_add_u32 s73, s50, 0x100
	v_mov_b32_e32 v0, 0
	s_addc_u32 s74, s51, 0
	s_mov_b32 s75, -2
	v_mov_b32_e32 v1, 0
	v_mov_b64_e32 v[2:3], 0
	v_mov_b64_e32 v[64:65], 0
	v_mov_b64_e32 v[66:67], 0
	v_mov_b64_e32 v[8:9], 0
	v_mov_b64_e32 v[10:11], 0
	v_mov_b64_e32 v[72:73], 0
	v_mov_b64_e32 v[74:75], 0
	v_mov_b64_e32 v[16:17], 0
	v_mov_b64_e32 v[18:19], 0
	v_mov_b64_e32 v[80:81], 0
	v_mov_b64_e32 v[82:83], 0
	v_mov_b64_e32 v[24:25], 0
	v_mov_b64_e32 v[26:27], 0
	v_mov_b64_e32 v[88:89], 0
	v_mov_b64_e32 v[90:91], 0
	v_mov_b64_e32 v[4:5], 0
	v_mov_b64_e32 v[6:7], 0
	v_mov_b64_e32 v[68:69], 0
	v_mov_b64_e32 v[70:71], 0
	v_mov_b64_e32 v[12:13], 0
	v_mov_b64_e32 v[14:15], 0
	v_mov_b64_e32 v[76:77], 0
	v_mov_b64_e32 v[78:79], 0
	v_mov_b64_e32 v[20:21], 0
	v_mov_b64_e32 v[22:23], 0
	v_mov_b64_e32 v[84:85], 0
	v_mov_b64_e32 v[86:87], 0
	v_mov_b64_e32 v[28:29], 0
	v_mov_b64_e32 v[30:31], 0
	v_mov_b64_e32 v[92:93], 0
	v_mov_b64_e32 v[94:95], 0
	v_mov_b64_e32 v[32:33], 0
	v_mov_b64_e32 v[34:35], 0
	v_mov_b64_e32 v[96:97], 0
	v_mov_b64_e32 v[98:99], 0
	v_mov_b64_e32 v[40:41], 0
	v_mov_b64_e32 v[42:43], 0
	v_mov_b64_e32 v[104:105], 0
	v_mov_b64_e32 v[106:107], 0
	v_mov_b64_e32 v[48:49], 0
	v_mov_b64_e32 v[50:51], 0
	v_mov_b64_e32 v[134:135], 0
	v_mov_b64_e32 v[136:137], 0
	v_mov_b64_e32 v[56:57], 0
	v_mov_b64_e32 v[58:59], 0
	v_mov_b64_e32 v[108:109], 0
	v_mov_b64_e32 v[110:111], 0
	v_mov_b64_e32 v[36:37], 0
	v_mov_b64_e32 v[38:39], 0
	v_mov_b64_e32 v[100:101], 0
	v_mov_b64_e32 v[102:103], 0
	v_mov_b64_e32 v[44:45], 0
	v_mov_b64_e32 v[46:47], 0
	v_mov_b64_e32 v[112:113], 0
	v_mov_b64_e32 v[114:115], 0
	v_mov_b64_e32 v[52:53], 0
	v_mov_b64_e32 v[54:55], 0
	v_mov_b64_e32 v[138:139], 0
	v_mov_b64_e32 v[140:141], 0
	v_mov_b64_e32 v[60:61], 0
	v_mov_b64_e32 v[62:63], 0
	v_mov_b64_e32 v[142:143], 0
	v_mov_b64_e32 v[144:145], 0

.LBB0_1104:
	v_mov_b32_e32 v228, 0xbfb8aa3b
	v_mov_b32_e32 v229, 0xbfb8aa3b
	v_mov_b32_e32 v230, 1.0
	v_mov_b32_e32 v231, 1.0
	v_readlane_b32 s90, v240, 36
	v_readlane_b32 s91, v240, 37
	v_readlane_b32 s35, v240, 38
	v_readlane_b32 s45, v240, 39
	v_cmp_eq_u32_e64 s[52:53], 0, v154
	s_add_u32 s74, s90, 0x0
	s_addc_u32 s75, s91, 0
	s_add_u32 s76, s90, 0x5800
	s_addc_u32 s77, s91, 0
	s_add_u32 s78, s90, 0xb000
	s_addc_u32 s79, s91, 0
	s_add_u32 s80, s90, 0x2c00
	s_addc_u32 s81, s91, 0
	s_add_u32 s82, s90, 0x8400
	s_addc_u32 s83, s91, 0
	s_add_u32 s84, s90, 0xdc00
	s_addc_u32 s85, s91, 0
	s_add_u32 s86, s35, 0
	s_addc_u32 s87, s45, 0
	s_add_u32 s88, s35, 0x2c00
	s_addc_u32 s89, s45, 0
	s_add_u32 s48, s94, 0x6500000
	s_addc_u32 s49, s95, 0
	s_add_u32 s50, s94, 0x1d600000
	s_addc_u32 s51, s95, 0
	v_lshl_or_b32 v128, s46, 7, v191
	s_lshl_b32 s47, s44, 8
	v_add_u32_e32 v129, s47, v155
	v_mul_u32_u24_e32 v129, 0x1600, v129
	v_lshl_add_u32 v129, v128, 1, v129
	v_lshlrev_b32_e32 v128, 2, v128
	global_load_dwordx4 v[196:199], v128, s[74:75]
	global_load_dwordx4 v[200:203], v128, s[76:77]
	global_load_dwordx4 v[204:207], v128, s[78:79]
	global_load_dwordx4 v[208:211], v128, s[86:87]
	global_load_dwordx4 v[212:215], v128, s[80:81]
	global_load_dwordx4 v[216:219], v128, s[82:83]
	global_load_dwordx4 v[220:223], v128, s[84:85]
	global_load_dwordx4 v[224:227], v128, s[88:89]
	s_lshl_b32 s47, s44, 4
	s_lshl_b32 s90, s33, 2
	s_add_i32 s47, s47, s90
	v_lshl_or_b32 v132, s46, 8, v191
	v_add_u32_e32 v130, s47, v154
	v_add_u32_e32 v131, s47, v156
	v_mul_u32_u24_e32 v130, 0x2c00, v130
	v_mul_u32_u24_e32 v131, 0x2c00, v131
	v_lshl_add_u32 v130, v132, 1, v130
	v_lshl_add_u32 v131, v132, 1, v131
	s_mov_b64 exec, s[0:1]
	v_cvt_pk_bf16_f32 v120, v142, v143
	v_cvt_pk_bf16_f32 v121, v144, v145
	v_cvt_pk_bf16_f32 v122, v60, v61
	v_cvt_pk_bf16_f32 v123, v62, v63
	global_store_dwordx4 v130, v[120:123], s[50:51]
	v_cvt_pk_bf16_f32 v124, v108, v109
	v_cvt_pk_bf16_f32 v125, v110, v111
	v_cvt_pk_bf16_f32 v126, v56, v57
	v_cvt_pk_bf16_f32 v127, v58, v59
	global_store_dwordx4 v130, v[124:127], s[50:51] offset:256
	s_mov_b64 exec, s[6:7]
	v_cvt_pk_bf16_f32 v120, v100, v101
	v_cvt_pk_bf16_f32 v121, v102, v103
	v_cvt_pk_bf16_f32 v122, v36, v37
	v_cvt_pk_bf16_f32 v123, v38, v39
	global_store_dwordx4 v131, v[120:123], s[50:51]
	v_cvt_pk_bf16_f32 v124, v96, v97
	v_cvt_pk_bf16_f32 v125, v98, v99
	v_cvt_pk_bf16_f32 v126, v32, v33
	v_cvt_pk_bf16_f32 v127, v34, v35
	global_store_dwordx4 v131, v[124:127], s[50:51] offset:256
	s_mov_b64 exec, s[0:1]
	v_cvt_pk_bf16_f32 v120, v92, v93
	v_cvt_pk_bf16_f32 v121, v94, v95
	v_cvt_pk_bf16_f32 v122, v28, v29
	v_cvt_pk_bf16_f32 v123, v30, v31
	v_add_u32_e32 v132, 0x16000, v130
	global_store_dwordx4 v132, v[120:123], s[50:51]
	v_cvt_pk_bf16_f32 v124, v88, v89
	v_cvt_pk_bf16_f32 v125, v90, v91
	v_cvt_pk_bf16_f32 v126, v24, v25
	v_cvt_pk_bf16_f32 v127, v26, v27
	v_add_u32_e32 v132, 0x16100, v130
	global_store_dwordx4 v132, v[124:127], s[50:51]
	s_mov_b64 exec, s[6:7]
	v_cvt_pk_bf16_f32 v120, v68, v69
	v_cvt_pk_bf16_f32 v121, v70, v71
	v_cvt_pk_bf16_f32 v122, v4, v5
	v_cvt_pk_bf16_f32 v123, v6, v7
	v_add_u32_e32 v132, 0x16000, v131
	global_store_dwordx4 v132, v[120:123], s[50:51]
	v_cvt_pk_bf16_f32 v124, v64, v65
	v_cvt_pk_bf16_f32 v125, v66, v67
	v_cvt_pk_bf16_f32 v126, v0, v1
	v_cvt_pk_bf16_f32 v127, v2, v3
	v_add_u32_e32 v132, 0x16100, v131
	global_store_dwordx4 v132, v[124:127], s[50:51]
	s_mov_b64 exec, -1
	s_waitcnt vmcnt(8)
	v_cndmask_b32_e64 v166, 0, v200, s[52:53]
	v_cndmask_b32_e64 v170, 0, v196, s[0:1]
	v_cndmask_b32_e64 v174, 0, v216, s[52:53]
	v_cndmask_b32_e64 v178, 0, v212, s[0:1]
	v_cndmask_b32_e64 v167, 0, v201, s[52:53]
	v_cndmask_b32_e64 v171, 0, v197, s[0:1]
	v_cndmask_b32_e64 v175, 0, v217, s[52:53]
	v_cndmask_b32_e64 v179, 0, v213, s[0:1]
	v_cndmask_b32_e64 v168, 0, v202, s[52:53]
	v_cndmask_b32_e64 v172, 0, v198, s[0:1]
	v_cndmask_b32_e64 v176, 0, v218, s[52:53]
	v_cndmask_b32_e64 v180, 0, v214, s[0:1]
	v_cndmask_b32_e64 v169, 0, v203, s[52:53]
	v_cndmask_b32_e64 v173, 0, v199, s[0:1]
	v_cndmask_b32_e64 v177, 0, v219, s[52:53]
	v_cndmask_b32_e64 v181, 0, v215, s[0:1]
	v_pk_fma_f32 v[182:183], v[204:205], v[100:101], v[208:209]
	v_pk_fma_f32 v[184:185], v[206:207], v[102:103], v[210:211]
	v_pk_fma_f32 v[186:187], v[220:221], v[96:97], v[224:225]
	v_pk_fma_f32 v[188:189], v[222:223], v[98:99], v[226:227]
	v_fmac_f32_dpp v182, v100, v200 row_shr:1 row_mask:0xf bank_mask:0xf
	v_fmac_f32_dpp v183, v101, v201 row_shr:1 row_mask:0xf bank_mask:0xf
	v_fmac_f32_dpp v184, v102, v202 row_shr:1 row_mask:0xf bank_mask:0xf
	v_fmac_f32_dpp v185, v103, v203 row_shr:1 row_mask:0xf bank_mask:0xf
	v_fmac_f32_dpp v186, v96, v216 row_shr:1 row_mask:0xf bank_mask:0xf
	v_fmac_f32_dpp v187, v97, v217 row_shr:1 row_mask:0xf bank_mask:0xf
	v_fmac_f32_dpp v188, v98, v218 row_shr:1 row_mask:0xf bank_mask:0xf
	v_fmac_f32_dpp v189, v99, v219 row_shr:1 row_mask:0xf bank_mask:0xf
	v_fmac_f32_dpp v182, v100, v196 row_shr:2 row_mask:0xf bank_mask:0xf
	v_fmac_f32_dpp v183, v101, v197 row_shr:2 row_mask:0xf bank_mask:0xf
	v_fmac_f32_dpp v184, v102, v198 row_shr:2 row_mask:0xf bank_mask:0xf
	v_fmac_f32_dpp v185, v103, v199 row_shr:2 row_mask:0xf bank_mask:0xf
	v_fmac_f32_dpp v186, v96, v212 row_shr:2 row_mask:0xf bank_mask:0xf
	v_fmac_f32_dpp v187, v97, v213 row_shr:2 row_mask:0xf bank_mask:0xf
	v_fmac_f32_dpp v188, v98, v214 row_shr:2 row_mask:0xf bank_mask:0xf
	v_fmac_f32_dpp v189, v99, v215 row_shr:2 row_mask:0xf bank_mask:0xf
	v_fmac_f32_dpp v182, v112, v166 row_ror:1 row_mask:0xf bank_mask:0xf
	v_fmac_f32_dpp v183, v113, v167 row_ror:1 row_mask:0xf bank_mask:0xf
	v_fmac_f32_dpp v184, v114, v168 row_ror:1 row_mask:0xf bank_mask:0xf
	v_fmac_f32_dpp v185, v115, v169 row_ror:1 row_mask:0xf bank_mask:0xf
	v_fmac_f32_dpp v186, v104, v174 row_ror:1 row_mask:0xf bank_mask:0xf
	v_fmac_f32_dpp v187, v105, v175 row_ror:1 row_mask:0xf bank_mask:0xf
	v_fmac_f32_dpp v188, v106, v176 row_ror:1 row_mask:0xf bank_mask:0xf
	v_fmac_f32_dpp v189, v107, v177 row_ror:1 row_mask:0xf bank_mask:0xf
	v_fmac_f32_dpp v182, v112, v170 row_ror:2 row_mask:0xf bank_mask:0xf
	v_fmac_f32_dpp v183, v113, v171 row_ror:2 row_mask:0xf bank_mask:0xf
	v_fmac_f32_dpp v184, v114, v172 row_ror:2 row_mask:0xf bank_mask:0xf
	v_fmac_f32_dpp v185, v115, v173 row_ror:2 row_mask:0xf bank_mask:0xf
	v_fmac_f32_dpp v186, v104, v178 row_ror:2 row_mask:0xf bank_mask:0xf
	v_fmac_f32_dpp v187, v105, v179 row_ror:2 row_mask:0xf bank_mask:0xf
	v_fmac_f32_dpp v188, v106, v180 row_ror:2 row_mask:0xf bank_mask:0xf
	v_fmac_f32_dpp v189, v107, v181 row_ror:2 row_mask:0xf bank_mask:0xf
	v_pk_mul_f32 v[116:117], v[182:183], v[228:229]
	v_pk_mul_f32 v[118:119], v[184:185], v[228:229]
	v_exp_f32_e32 v116, v116
	v_exp_f32_e32 v117, v117
	v_exp_f32_e32 v118, v118
	v_exp_f32_e32 v119, v119
	v_pk_add_f32 v[116:117], v[116:117], v[230:231]
	v_pk_add_f32 v[118:119], v[118:119], v[230:231]
	v_rcp_f32_e32 v116, v116
	v_rcp_f32_e32 v117, v117
	v_rcp_f32_e32 v118, v118
	v_rcp_f32_e32 v119, v119
	v_pk_mul_f32 v[116:117], v[182:183], v[116:117]
	v_pk_mul_f32 v[118:119], v[184:185], v[118:119]
	v_pk_mul_f32 v[116:117], v[116:117], v[186:187]
	v_pk_mul_f32 v[118:119], v[118:119], v[188:189]
	v_cvt_pk_bf16_f32 v100, v116, v117
	v_cvt_pk_bf16_f32 v101, v118, v119
	v_pk_fma_f32 v[182:183], v[204:205], v[112:113], v[208:209]
	v_pk_fma_f32 v[184:185], v[206:207], v[114:115], v[210:211]
	v_pk_fma_f32 v[186:187], v[220:221], v[104:105], v[224:225]
	v_pk_fma_f32 v[188:189], v[222:223], v[106:107], v[226:227]
	v_fmac_f32_dpp v182, v112, v200 row_shr:1 row_mask:0xf bank_mask:0xf
	v_fmac_f32_dpp v183, v113, v201 row_shr:1 row_mask:0xf bank_mask:0xf
	v_fmac_f32_dpp v184, v114, v202 row_shr:1 row_mask:0xf bank_mask:0xf
	v_fmac_f32_dpp v185, v115, v203 row_shr:1 row_mask:0xf bank_mask:0xf
	v_fmac_f32_dpp v186, v104, v216 row_shr:1 row_mask:0xf bank_mask:0xf
	v_fmac_f32_dpp v187, v105, v217 row_shr:1 row_mask:0xf bank_mask:0xf
	v_fmac_f32_dpp v188, v106, v218 row_shr:1 row_mask:0xf bank_mask:0xf
	v_fmac_f32_dpp v189, v107, v219 row_shr:1 row_mask:0xf bank_mask:0xf
	v_fmac_f32_dpp v182, v112, v196 row_shr:2 row_mask:0xf bank_mask:0xf
	v_fmac_f32_dpp v183, v113, v197 row_shr:2 row_mask:0xf bank_mask:0xf
	v_fmac_f32_dpp v184, v114, v198 row_shr:2 row_mask:0xf bank_mask:0xf
	v_fmac_f32_dpp v185, v115, v199 row_shr:2 row_mask:0xf bank_mask:0xf
	v_fmac_f32_dpp v186, v104, v212 row_shr:2 row_mask:0xf bank_mask:0xf
	v_fmac_f32_dpp v187, v105, v213 row_shr:2 row_mask:0xf bank_mask:0xf
	v_fmac_f32_dpp v188, v106, v214 row_shr:2 row_mask:0xf bank_mask:0xf
	v_fmac_f32_dpp v189, v107, v215 row_shr:2 row_mask:0xf bank_mask:0xf
	v_fmac_f32_dpp v182, v138, v166 row_ror:1 row_mask:0xf bank_mask:0xf
	v_fmac_f32_dpp v183, v139, v167 row_ror:1 row_mask:0xf bank_mask:0xf
	v_fmac_f32_dpp v184, v140, v168 row_ror:1 row_mask:0xf bank_mask:0xf
	v_fmac_f32_dpp v185, v141, v169 row_ror:1 row_mask:0xf bank_mask:0xf
	v_fmac_f32_dpp v186, v134, v174 row_ror:1 row_mask:0xf bank_mask:0xf
	v_fmac_f32_dpp v187, v135, v175 row_ror:1 row_mask:0xf bank_mask:0xf
	v_fmac_f32_dpp v188, v136, v176 row_ror:1 row_mask:0xf bank_mask:0xf
	v_fmac_f32_dpp v189, v137, v177 row_ror:1 row_mask:0xf bank_mask:0xf
	v_fmac_f32_dpp v182, v138, v170 row_ror:2 row_mask:0xf bank_mask:0xf
	v_fmac_f32_dpp v183, v139, v171 row_ror:2 row_mask:0xf bank_mask:0xf
	v_fmac_f32_dpp v184, v140, v172 row_ror:2 row_mask:0xf bank_mask:0xf
	v_fmac_f32_dpp v185, v141, v173 row_ror:2 row_mask:0xf bank_mask:0xf
	v_fmac_f32_dpp v186, v134, v178 row_ror:2 row_mask:0xf bank_mask:0xf
	v_fmac_f32_dpp v187, v135, v179 row_ror:2 row_mask:0xf bank_mask:0xf
	v_fmac_f32_dpp v188, v136, v180 row_ror:2 row_mask:0xf bank_mask:0xf
	v_fmac_f32_dpp v189, v137, v181 row_ror:2 row_mask:0xf bank_mask:0xf
	v_pk_mul_f32 v[116:117], v[182:183], v[228:229]
	v_pk_mul_f32 v[118:119], v[184:185], v[228:229]
	v_exp_f32_e32 v116, v116
	v_exp_f32_e32 v117, v117
	v_exp_f32_e32 v118, v118
	v_exp_f32_e32 v119, v119
	v_pk_add_f32 v[116:117], v[116:117], v[230:231]
	v_pk_add_f32 v[118:119], v[118:119], v[230:231]
	v_rcp_f32_e32 v116, v116
	v_rcp_f32_e32 v117, v117
	v_rcp_f32_e32 v118, v118
	v_rcp_f32_e32 v119, v119
	v_pk_mul_f32 v[116:117], v[182:183], v[116:117]
	v_pk_mul_f32 v[118:119], v[184:185], v[118:119]
	v_pk_mul_f32 v[116:117], v[116:117], v[186:187]
	v_pk_mul_f32 v[118:119], v[118:119], v[188:189]
	v_cvt_pk_bf16_f32 v112, v116, v117
	v_cvt_pk_bf16_f32 v113, v118, v119
	v_pk_fma_f32 v[182:183], v[204:205], v[138:139], v[208:209]
	v_pk_fma_f32 v[184:185], v[206:207], v[140:141], v[210:211]
	v_pk_fma_f32 v[186:187], v[220:221], v[134:135], v[224:225]
	v_pk_fma_f32 v[188:189], v[222:223], v[136:137], v[226:227]
	v_fmac_f32_dpp v182, v138, v200 row_shr:1 row_mask:0xf bank_mask:0xf
	v_fmac_f32_dpp v183, v139, v201 row_shr:1 row_mask:0xf bank_mask:0xf
	v_fmac_f32_dpp v184, v140, v202 row_shr:1 row_mask:0xf bank_mask:0xf
	v_fmac_f32_dpp v185, v141, v203 row_shr:1 row_mask:0xf bank_mask:0xf
	v_fmac_f32_dpp v186, v134, v216 row_shr:1 row_mask:0xf bank_mask:0xf
	v_fmac_f32_dpp v187, v135, v217 row_shr:1 row_mask:0xf bank_mask:0xf
	v_fmac_f32_dpp v188, v136, v218 row_shr:1 row_mask:0xf bank_mask:0xf
	v_fmac_f32_dpp v189, v137, v219 row_shr:1 row_mask:0xf bank_mask:0xf
	v_fmac_f32_dpp v182, v138, v196 row_shr:2 row_mask:0xf bank_mask:0xf
	v_fmac_f32_dpp v183, v139, v197 row_shr:2 row_mask:0xf bank_mask:0xf
	v_fmac_f32_dpp v184, v140, v198 row_shr:2 row_mask:0xf bank_mask:0xf
	v_fmac_f32_dpp v185, v141, v199 row_shr:2 row_mask:0xf bank_mask:0xf
	v_fmac_f32_dpp v186, v134, v212 row_shr:2 row_mask:0xf bank_mask:0xf
	v_fmac_f32_dpp v187, v135, v213 row_shr:2 row_mask:0xf bank_mask:0xf
	v_fmac_f32_dpp v188, v136, v214 row_shr:2 row_mask:0xf bank_mask:0xf
	v_fmac_f32_dpp v189, v137, v215 row_shr:2 row_mask:0xf bank_mask:0xf
	v_fmac_f32_dpp v182, v142, v166 row_ror:1 row_mask:0xf bank_mask:0xf
	v_fmac_f32_dpp v183, v143, v167 row_ror:1 row_mask:0xf bank_mask:0xf
	v_fmac_f32_dpp v184, v144, v168 row_ror:1 row_mask:0xf bank_mask:0xf
	v_fmac_f32_dpp v185, v145, v169 row_ror:1 row_mask:0xf bank_mask:0xf
	v_fmac_f32_dpp v186, v108, v174 row_ror:1 row_mask:0xf bank_mask:0xf
	v_fmac_f32_dpp v187, v109, v175 row_ror:1 row_mask:0xf bank_mask:0xf
	v_fmac_f32_dpp v188, v110, v176 row_ror:1 row_mask:0xf bank_mask:0xf
	v_fmac_f32_dpp v189, v111, v177 row_ror:1 row_mask:0xf bank_mask:0xf
	v_fmac_f32_dpp v182, v142, v170 row_ror:2 row_mask:0xf bank_mask:0xf
	v_fmac_f32_dpp v183, v143, v171 row_ror:2 row_mask:0xf bank_mask:0xf
	v_fmac_f32_dpp v184, v144, v172 row_ror:2 row_mask:0xf bank_mask:0xf
	v_fmac_f32_dpp v185, v145, v173 row_ror:2 row_mask:0xf bank_mask:0xf
	v_fmac_f32_dpp v186, v108, v178 row_ror:2 row_mask:0xf bank_mask:0xf
	v_fmac_f32_dpp v187, v109, v179 row_ror:2 row_mask:0xf bank_mask:0xf
	v_fmac_f32_dpp v188, v110, v180 row_ror:2 row_mask:0xf bank_mask:0xf
	v_fmac_f32_dpp v189, v111, v181 row_ror:2 row_mask:0xf bank_mask:0xf
	v_pk_mul_f32 v[116:117], v[182:183], v[228:229]
	v_pk_mul_f32 v[118:119], v[184:185], v[228:229]
	v_exp_f32_e32 v116, v116
	v_exp_f32_e32 v117, v117
	v_exp_f32_e32 v118, v118
	v_exp_f32_e32 v119, v119
	v_pk_add_f32 v[116:117], v[116:117], v[230:231]
	v_pk_add_f32 v[118:119], v[118:119], v[230:231]
	v_rcp_f32_e32 v116, v116
	v_rcp_f32_e32 v117, v117
	v_rcp_f32_e32 v118, v118
	v_rcp_f32_e32 v119, v119
	v_pk_mul_f32 v[116:117], v[182:183], v[116:117]
	v_pk_mul_f32 v[118:119], v[184:185], v[118:119]
	v_pk_mul_f32 v[116:117], v[116:117], v[186:187]
	v_pk_mul_f32 v[118:119], v[118:119], v[188:189]
	v_cvt_pk_bf16_f32 v138, v116, v117
	v_cvt_pk_bf16_f32 v139, v118, v119
	v_pk_fma_f32 v[182:183], v[204:205], v[142:143], v[208:209]
	v_pk_fma_f32 v[184:185], v[206:207], v[144:145], v[210:211]
	v_pk_fma_f32 v[186:187], v[220:221], v[108:109], v[224:225]
	v_pk_fma_f32 v[188:189], v[222:223], v[110:111], v[226:227]
	v_fmac_f32_dpp v182, v142, v200 row_shr:1 row_mask:0xf bank_mask:0xf
	v_fmac_f32_dpp v183, v143, v201 row_shr:1 row_mask:0xf bank_mask:0xf
	v_fmac_f32_dpp v184, v144, v202 row_shr:1 row_mask:0xf bank_mask:0xf
	v_fmac_f32_dpp v185, v145, v203 row_shr:1 row_mask:0xf bank_mask:0xf
	v_fmac_f32_dpp v186, v108, v216 row_shr:1 row_mask:0xf bank_mask:0xf
	v_fmac_f32_dpp v187, v109, v217 row_shr:1 row_mask:0xf bank_mask:0xf
	v_fmac_f32_dpp v188, v110, v218 row_shr:1 row_mask:0xf bank_mask:0xf
	v_fmac_f32_dpp v189, v111, v219 row_shr:1 row_mask:0xf bank_mask:0xf
	v_fmac_f32_dpp v182, v142, v196 row_shr:2 row_mask:0xf bank_mask:0xf
	v_fmac_f32_dpp v183, v143, v197 row_shr:2 row_mask:0xf bank_mask:0xf
	v_fmac_f32_dpp v184, v144, v198 row_shr:2 row_mask:0xf bank_mask:0xf
	v_fmac_f32_dpp v185, v145, v199 row_shr:2 row_mask:0xf bank_mask:0xf
	v_fmac_f32_dpp v186, v108, v212 row_shr:2 row_mask:0xf bank_mask:0xf
	v_fmac_f32_dpp v187, v109, v213 row_shr:2 row_mask:0xf bank_mask:0xf
	v_fmac_f32_dpp v188, v110, v214 row_shr:2 row_mask:0xf bank_mask:0xf
	v_fmac_f32_dpp v189, v111, v215 row_shr:2 row_mask:0xf bank_mask:0xf
	v_pk_mul_f32 v[116:117], v[182:183], v[228:229]
	v_pk_mul_f32 v[118:119], v[184:185], v[228:229]
	v_exp_f32_e32 v116, v116
	v_exp_f32_e32 v117, v117
	v_exp_f32_e32 v118, v118
	v_exp_f32_e32 v119, v119
	v_pk_add_f32 v[116:117], v[116:117], v[230:231]
	v_pk_add_f32 v[118:119], v[118:119], v[230:231]
	v_rcp_f32_e32 v116, v116
	v_rcp_f32_e32 v117, v117
	v_rcp_f32_e32 v118, v118
	v_rcp_f32_e32 v119, v119
	v_pk_mul_f32 v[116:117], v[182:183], v[116:117]
	v_pk_mul_f32 v[118:119], v[184:185], v[118:119]
	v_pk_mul_f32 v[116:117], v[116:117], v[186:187]
	v_pk_mul_f32 v[118:119], v[118:119], v[188:189]
	v_cvt_pk_bf16_f32 v142, v116, v117
	v_cvt_pk_bf16_f32 v143, v118, v119
	v_pk_fma_f32 v[182:183], v[204:205], v[68:69], v[208:209]
	v_pk_fma_f32 v[184:185], v[206:207], v[70:71], v[210:211]
	v_pk_fma_f32 v[186:187], v[220:221], v[64:65], v[224:225]
	v_pk_fma_f32 v[188:189], v[222:223], v[66:67], v[226:227]
	v_fmac_f32_dpp v182, v68, v200 row_shr:1 row_mask:0xf bank_mask:0xf
	v_fmac_f32_dpp v183, v69, v201 row_shr:1 row_mask:0xf bank_mask:0xf
	v_fmac_f32_dpp v184, v70, v202 row_shr:1 row_mask:0xf bank_mask:0xf
	v_fmac_f32_dpp v185, v71, v203 row_shr:1 row_mask:0xf bank_mask:0xf
	v_fmac_f32_dpp v186, v64, v216 row_shr:1 row_mask:0xf bank_mask:0xf
	v_fmac_f32_dpp v187, v65, v217 row_shr:1 row_mask:0xf bank_mask:0xf
	v_fmac_f32_dpp v188, v66, v218 row_shr:1 row_mask:0xf bank_mask:0xf
	v_fmac_f32_dpp v189, v67, v219 row_shr:1 row_mask:0xf bank_mask:0xf
	v_fmac_f32_dpp v182, v68, v196 row_shr:2 row_mask:0xf bank_mask:0xf
	v_fmac_f32_dpp v183, v69, v197 row_shr:2 row_mask:0xf bank_mask:0xf
	v_fmac_f32_dpp v184, v70, v198 row_shr:2 row_mask:0xf bank_mask:0xf
	v_fmac_f32_dpp v185, v71, v199 row_shr:2 row_mask:0xf bank_mask:0xf
	v_fmac_f32_dpp v186, v64, v212 row_shr:2 row_mask:0xf bank_mask:0xf
	v_fmac_f32_dpp v187, v65, v213 row_shr:2 row_mask:0xf bank_mask:0xf
	v_fmac_f32_dpp v188, v66, v214 row_shr:2 row_mask:0xf bank_mask:0xf
	v_fmac_f32_dpp v189, v67, v215 row_shr:2 row_mask:0xf bank_mask:0xf
	v_fmac_f32_dpp v182, v76, v166 row_ror:1 row_mask:0xf bank_mask:0xf
	v_fmac_f32_dpp v183, v77, v167 row_ror:1 row_mask:0xf bank_mask:0xf
	v_fmac_f32_dpp v184, v78, v168 row_ror:1 row_mask:0xf bank_mask:0xf
	v_fmac_f32_dpp v185, v79, v169 row_ror:1 row_mask:0xf bank_mask:0xf
	v_fmac_f32_dpp v186, v72, v174 row_ror:1 row_mask:0xf bank_mask:0xf
	v_fmac_f32_dpp v187, v73, v175 row_ror:1 row_mask:0xf bank_mask:0xf
	v_fmac_f32_dpp v188, v74, v176 row_ror:1 row_mask:0xf bank_mask:0xf
	v_fmac_f32_dpp v189, v75, v177 row_ror:1 row_mask:0xf bank_mask:0xf
	v_fmac_f32_dpp v182, v76, v170 row_ror:2 row_mask:0xf bank_mask:0xf
	v_fmac_f32_dpp v183, v77, v171 row_ror:2 row_mask:0xf bank_mask:0xf
	v_fmac_f32_dpp v184, v78, v172 row_ror:2 row_mask:0xf bank_mask:0xf
	v_fmac_f32_dpp v185, v79, v173 row_ror:2 row_mask:0xf bank_mask:0xf
	v_fmac_f32_dpp v186, v72, v178 row_ror:2 row_mask:0xf bank_mask:0xf
	v_fmac_f32_dpp v187, v73, v179 row_ror:2 row_mask:0xf bank_mask:0xf
	v_fmac_f32_dpp v188, v74, v180 row_ror:2 row_mask:0xf bank_mask:0xf
	v_fmac_f32_dpp v189, v75, v181 row_ror:2 row_mask:0xf bank_mask:0xf
	v_pk_mul_f32 v[116:117], v[182:183], v[228:229]
	v_pk_mul_f32 v[118:119], v[184:185], v[228:229]
	v_exp_f32_e32 v116, v116
	v_exp_f32_e32 v117, v117
	v_exp_f32_e32 v118, v118
	v_exp_f32_e32 v119, v119
	v_pk_add_f32 v[116:117], v[116:117], v[230:231]
	v_pk_add_f32 v[118:119], v[118:119], v[230:231]
	v_rcp_f32_e32 v116, v116
	v_rcp_f32_e32 v117, v117
	v_rcp_f32_e32 v118, v118
	v_rcp_f32_e32 v119, v119
	v_pk_mul_f32 v[116:117], v[182:183], v[116:117]
	v_pk_mul_f32 v[118:119], v[184:185], v[118:119]
	v_pk_mul_f32 v[116:117], v[116:117], v[186:187]
	v_pk_mul_f32 v[118:119], v[118:119], v[188:189]
	v_cvt_pk_bf16_f32 v68, v116, v117
	v_cvt_pk_bf16_f32 v69, v118, v119
	v_pk_fma_f32 v[182:183], v[204:205], v[76:77], v[208:209]
	v_pk_fma_f32 v[184:185], v[206:207], v[78:79], v[210:211]
	v_pk_fma_f32 v[186:187], v[220:221], v[72:73], v[224:225]
	v_pk_fma_f32 v[188:189], v[222:223], v[74:75], v[226:227]
	v_fmac_f32_dpp v182, v76, v200 row_shr:1 row_mask:0xf bank_mask:0xf
	v_fmac_f32_dpp v183, v77, v201 row_shr:1 row_mask:0xf bank_mask:0xf
	v_fmac_f32_dpp v184, v78, v202 row_shr:1 row_mask:0xf bank_mask:0xf
	v_fmac_f32_dpp v185, v79, v203 row_shr:1 row_mask:0xf bank_mask:0xf
	v_fmac_f32_dpp v186, v72, v216 row_shr:1 row_mask:0xf bank_mask:0xf
	v_fmac_f32_dpp v187, v73, v217 row_shr:1 row_mask:0xf bank_mask:0xf
	v_fmac_f32_dpp v188, v74, v218 row_shr:1 row_mask:0xf bank_mask:0xf
	v_fmac_f32_dpp v189, v75, v219 row_shr:1 row_mask:0xf bank_mask:0xf
	v_fmac_f32_dpp v182, v76, v196 row_shr:2 row_mask:0xf bank_mask:0xf
	v_fmac_f32_dpp v183, v77, v197 row_shr:2 row_mask:0xf bank_mask:0xf
	v_fmac_f32_dpp v184, v78, v198 row_shr:2 row_mask:0xf bank_mask:0xf
	v_fmac_f32_dpp v185, v79, v199 row_shr:2 row_mask:0xf bank_mask:0xf
	v_fmac_f32_dpp v186, v72, v212 row_shr:2 row_mask:0xf bank_mask:0xf
	v_fmac_f32_dpp v187, v73, v213 row_shr:2 row_mask:0xf bank_mask:0xf
	v_fmac_f32_dpp v188, v74, v214 row_shr:2 row_mask:0xf bank_mask:0xf
	v_fmac_f32_dpp v189, v75, v215 row_shr:2 row_mask:0xf bank_mask:0xf
	v_fmac_f32_dpp v182, v84, v166 row_ror:1 row_mask:0xf bank_mask:0xf
	v_fmac_f32_dpp v183, v85, v167 row_ror:1 row_mask:0xf bank_mask:0xf
	v_fmac_f32_dpp v184, v86, v168 row_ror:1 row_mask:0xf bank_mask:0xf
	v_fmac_f32_dpp v185, v87, v169 row_ror:1 row_mask:0xf bank_mask:0xf
	v_fmac_f32_dpp v186, v80, v174 row_ror:1 row_mask:0xf bank_mask:0xf
	v_fmac_f32_dpp v187, v81, v175 row_ror:1 row_mask:0xf bank_mask:0xf
	v_fmac_f32_dpp v188, v82, v176 row_ror:1 row_mask:0xf bank_mask:0xf
	v_fmac_f32_dpp v189, v83, v177 row_ror:1 row_mask:0xf bank_mask:0xf
	v_fmac_f32_dpp v182, v84, v170 row_ror:2 row_mask:0xf bank_mask:0xf
	v_fmac_f32_dpp v183, v85, v171 row_ror:2 row_mask:0xf bank_mask:0xf
	v_fmac_f32_dpp v184, v86, v172 row_ror:2 row_mask:0xf bank_mask:0xf
	v_fmac_f32_dpp v185, v87, v173 row_ror:2 row_mask:0xf bank_mask:0xf
	v_fmac_f32_dpp v186, v80, v178 row_ror:2 row_mask:0xf bank_mask:0xf
	v_fmac_f32_dpp v187, v81, v179 row_ror:2 row_mask:0xf bank_mask:0xf
	v_fmac_f32_dpp v188, v82, v180 row_ror:2 row_mask:0xf bank_mask:0xf
	v_fmac_f32_dpp v189, v83, v181 row_ror:2 row_mask:0xf bank_mask:0xf
	v_pk_mul_f32 v[116:117], v[182:183], v[228:229]
	v_pk_mul_f32 v[118:119], v[184:185], v[228:229]
	v_exp_f32_e32 v116, v116
	v_exp_f32_e32 v117, v117
	v_exp_f32_e32 v118, v118
	v_exp_f32_e32 v119, v119
	v_pk_add_f32 v[116:117], v[116:117], v[230:231]
	v_pk_add_f32 v[118:119], v[118:119], v[230:231]
	v_rcp_f32_e32 v116, v116
	v_rcp_f32_e32 v117, v117
	v_rcp_f32_e32 v118, v118
	v_rcp_f32_e32 v119, v119
	v_pk_mul_f32 v[116:117], v[182:183], v[116:117]
	v_pk_mul_f32 v[118:119], v[184:185], v[118:119]
	v_pk_mul_f32 v[116:117], v[116:117], v[186:187]
	v_pk_mul_f32 v[118:119], v[118:119], v[188:189]
	v_cvt_pk_bf16_f32 v76, v116, v117
	v_cvt_pk_bf16_f32 v77, v118, v119
	v_pk_fma_f32 v[182:183], v[204:205], v[84:85], v[208:209]
	v_pk_fma_f32 v[184:185], v[206:207], v[86:87], v[210:211]
	v_pk_fma_f32 v[186:187], v[220:221], v[80:81], v[224:225]
	v_pk_fma_f32 v[188:189], v[222:223], v[82:83], v[226:227]
	v_fmac_f32_dpp v182, v84, v200 row_shr:1 row_mask:0xf bank_mask:0xf
	v_fmac_f32_dpp v183, v85, v201 row_shr:1 row_mask:0xf bank_mask:0xf
	v_fmac_f32_dpp v184, v86, v202 row_shr:1 row_mask:0xf bank_mask:0xf
	v_fmac_f32_dpp v185, v87, v203 row_shr:1 row_mask:0xf bank_mask:0xf
	v_fmac_f32_dpp v186, v80, v216 row_shr:1 row_mask:0xf bank_mask:0xf
	v_fmac_f32_dpp v187, v81, v217 row_shr:1 row_mask:0xf bank_mask:0xf
	v_fmac_f32_dpp v188, v82, v218 row_shr:1 row_mask:0xf bank_mask:0xf
	v_fmac_f32_dpp v189, v83, v219 row_shr:1 row_mask:0xf bank_mask:0xf
	v_fmac_f32_dpp v182, v84, v196 row_shr:2 row_mask:0xf bank_mask:0xf
	v_fmac_f32_dpp v183, v85, v197 row_shr:2 row_mask:0xf bank_mask:0xf
	v_fmac_f32_dpp v184, v86, v198 row_shr:2 row_mask:0xf bank_mask:0xf
	v_fmac_f32_dpp v185, v87, v199 row_shr:2 row_mask:0xf bank_mask:0xf
	v_fmac_f32_dpp v186, v80, v212 row_shr:2 row_mask:0xf bank_mask:0xf
	v_fmac_f32_dpp v187, v81, v213 row_shr:2 row_mask:0xf bank_mask:0xf
	v_fmac_f32_dpp v188, v82, v214 row_shr:2 row_mask:0xf bank_mask:0xf
	v_fmac_f32_dpp v189, v83, v215 row_shr:2 row_mask:0xf bank_mask:0xf
	v_fmac_f32_dpp v182, v92, v166 row_ror:1 row_mask:0xf bank_mask:0xf
	v_fmac_f32_dpp v183, v93, v167 row_ror:1 row_mask:0xf bank_mask:0xf
	v_fmac_f32_dpp v184, v94, v168 row_ror:1 row_mask:0xf bank_mask:0xf
	v_fmac_f32_dpp v185, v95, v169 row_ror:1 row_mask:0xf bank_mask:0xf
	v_fmac_f32_dpp v186, v88, v174 row_ror:1 row_mask:0xf bank_mask:0xf
	v_fmac_f32_dpp v187, v89, v175 row_ror:1 row_mask:0xf bank_mask:0xf
	v_fmac_f32_dpp v188, v90, v176 row_ror:1 row_mask:0xf bank_mask:0xf
	v_fmac_f32_dpp v189, v91, v177 row_ror:1 row_mask:0xf bank_mask:0xf
	v_fmac_f32_dpp v182, v92, v170 row_ror:2 row_mask:0xf bank_mask:0xf
	v_fmac_f32_dpp v183, v93, v171 row_ror:2 row_mask:0xf bank_mask:0xf
	v_fmac_f32_dpp v184, v94, v172 row_ror:2 row_mask:0xf bank_mask:0xf
	v_fmac_f32_dpp v185, v95, v173 row_ror:2 row_mask:0xf bank_mask:0xf
	v_fmac_f32_dpp v186, v88, v178 row_ror:2 row_mask:0xf bank_mask:0xf
	v_fmac_f32_dpp v187, v89, v179 row_ror:2 row_mask:0xf bank_mask:0xf
	v_fmac_f32_dpp v188, v90, v180 row_ror:2 row_mask:0xf bank_mask:0xf
	v_fmac_f32_dpp v189, v91, v181 row_ror:2 row_mask:0xf bank_mask:0xf
	v_pk_mul_f32 v[116:117], v[182:183], v[228:229]
	v_pk_mul_f32 v[118:119], v[184:185], v[228:229]
	v_exp_f32_e32 v116, v116
	v_exp_f32_e32 v117, v117
	v_exp_f32_e32 v118, v118
	v_exp_f32_e32 v119, v119
	v_pk_add_f32 v[116:117], v[116:117], v[230:231]
	v_pk_add_f32 v[118:119], v[118:119], v[230:231]
	v_rcp_f32_e32 v116, v116
	v_rcp_f32_e32 v117, v117
	v_rcp_f32_e32 v118, v118
	v_rcp_f32_e32 v119, v119
	v_pk_mul_f32 v[116:117], v[182:183], v[116:117]
	v_pk_mul_f32 v[118:119], v[184:185], v[118:119]
	v_pk_mul_f32 v[116:117], v[116:117], v[186:187]
	v_pk_mul_f32 v[118:119], v[118:119], v[188:189]
	v_cvt_pk_bf16_f32 v84, v116, v117
	v_cvt_pk_bf16_f32 v85, v118, v119
	v_pk_fma_f32 v[182:183], v[204:205], v[92:93], v[208:209]
	v_pk_fma_f32 v[184:185], v[206:207], v[94:95], v[210:211]
	v_pk_fma_f32 v[186:187], v[220:221], v[88:89], v[224:225]
	v_pk_fma_f32 v[188:189], v[222:223], v[90:91], v[226:227]
	v_fmac_f32_dpp v182, v92, v200 row_shr:1 row_mask:0xf bank_mask:0xf
	v_fmac_f32_dpp v183, v93, v201 row_shr:1 row_mask:0xf bank_mask:0xf
	v_fmac_f32_dpp v184, v94, v202 row_shr:1 row_mask:0xf bank_mask:0xf
	v_fmac_f32_dpp v185, v95, v203 row_shr:1 row_mask:0xf bank_mask:0xf
	v_fmac_f32_dpp v186, v88, v216 row_shr:1 row_mask:0xf bank_mask:0xf
	v_fmac_f32_dpp v187, v89, v217 row_shr:1 row_mask:0xf bank_mask:0xf
	v_fmac_f32_dpp v188, v90, v218 row_shr:1 row_mask:0xf bank_mask:0xf
	v_fmac_f32_dpp v189, v91, v219 row_shr:1 row_mask:0xf bank_mask:0xf
	v_fmac_f32_dpp v182, v92, v196 row_shr:2 row_mask:0xf bank_mask:0xf
	v_fmac_f32_dpp v183, v93, v197 row_shr:2 row_mask:0xf bank_mask:0xf
	v_fmac_f32_dpp v184, v94, v198 row_shr:2 row_mask:0xf bank_mask:0xf
	v_fmac_f32_dpp v185, v95, v199 row_shr:2 row_mask:0xf bank_mask:0xf
	v_fmac_f32_dpp v186, v88, v212 row_shr:2 row_mask:0xf bank_mask:0xf
	v_fmac_f32_dpp v187, v89, v213 row_shr:2 row_mask:0xf bank_mask:0xf
	v_fmac_f32_dpp v188, v90, v214 row_shr:2 row_mask:0xf bank_mask:0xf
	v_fmac_f32_dpp v189, v91, v215 row_shr:2 row_mask:0xf bank_mask:0xf
	global_load_dwordx4 v[196:199], v128, s[74:75] offset:16
	global_load_dwordx4 v[200:203], v128, s[76:77] offset:16
	global_load_dwordx4 v[204:207], v128, s[78:79] offset:16
	global_load_dwordx4 v[208:211], v128, s[86:87] offset:16
	global_load_dwordx4 v[212:215], v128, s[80:81] offset:16
	global_load_dwordx4 v[216:219], v128, s[82:83] offset:16
	global_load_dwordx4 v[220:223], v128, s[84:85] offset:16
	global_load_dwordx4 v[224:227], v128, s[88:89] offset:16
	v_pk_mul_f32 v[116:117], v[182:183], v[228:229]
	v_pk_mul_f32 v[118:119], v[184:185], v[228:229]
	v_exp_f32_e32 v116, v116
	v_exp_f32_e32 v117, v117
	v_exp_f32_e32 v118, v118
	v_exp_f32_e32 v119, v119
	v_pk_add_f32 v[116:117], v[116:117], v[230:231]
	v_pk_add_f32 v[118:119], v[118:119], v[230:231]
	v_rcp_f32_e32 v116, v116
	v_rcp_f32_e32 v117, v117
	v_rcp_f32_e32 v118, v118
	v_rcp_f32_e32 v119, v119
	v_pk_mul_f32 v[116:117], v[182:183], v[116:117]
	v_pk_mul_f32 v[118:119], v[184:185], v[118:119]
	v_pk_mul_f32 v[116:117], v[116:117], v[186:187]
	v_pk_mul_f32 v[118:119], v[118:119], v[188:189]
	v_cvt_pk_bf16_f32 v92, v116, v117
	v_cvt_pk_bf16_f32 v93, v118, v119
	s_waitcnt vmcnt(0)
	v_cndmask_b32_e64 v166, 0, v200, s[52:53]
	v_cndmask_b32_e64 v170, 0, v196, s[0:1]
	v_cndmask_b32_e64 v174, 0, v216, s[52:53]
	v_cndmask_b32_e64 v178, 0, v212, s[0:1]
	v_cndmask_b32_e64 v167, 0, v201, s[52:53]
	v_cndmask_b32_e64 v171, 0, v197, s[0:1]
	v_cndmask_b32_e64 v175, 0, v217, s[52:53]
	v_cndmask_b32_e64 v179, 0, v213, s[0:1]
	v_cndmask_b32_e64 v168, 0, v202, s[52:53]
	v_cndmask_b32_e64 v172, 0, v198, s[0:1]
	v_cndmask_b32_e64 v176, 0, v218, s[52:53]
	v_cndmask_b32_e64 v180, 0, v214, s[0:1]
	v_cndmask_b32_e64 v169, 0, v203, s[52:53]
	v_cndmask_b32_e64 v173, 0, v199, s[0:1]
	v_cndmask_b32_e64 v177, 0, v219, s[52:53]
	v_cndmask_b32_e64 v181, 0, v215, s[0:1]
	v_pk_fma_f32 v[182:183], v[204:205], v[36:37], v[208:209]
	v_pk_fma_f32 v[184:185], v[206:207], v[38:39], v[210:211]
	v_pk_fma_f32 v[186:187], v[220:221], v[32:33], v[224:225]
	v_pk_fma_f32 v[188:189], v[222:223], v[34:35], v[226:227]
	v_fmac_f32_dpp v182, v36, v200 row_shr:1 row_mask:0xf bank_mask:0xf
	v_fmac_f32_dpp v183, v37, v201 row_shr:1 row_mask:0xf bank_mask:0xf
	v_fmac_f32_dpp v184, v38, v202 row_shr:1 row_mask:0xf bank_mask:0xf
	v_fmac_f32_dpp v185, v39, v203 row_shr:1 row_mask:0xf bank_mask:0xf
	v_fmac_f32_dpp v186, v32, v216 row_shr:1 row_mask:0xf bank_mask:0xf
	v_fmac_f32_dpp v187, v33, v217 row_shr:1 row_mask:0xf bank_mask:0xf
	v_fmac_f32_dpp v188, v34, v218 row_shr:1 row_mask:0xf bank_mask:0xf
	v_fmac_f32_dpp v189, v35, v219 row_shr:1 row_mask:0xf bank_mask:0xf
	v_fmac_f32_dpp v182, v36, v196 row_shr:2 row_mask:0xf bank_mask:0xf
	v_fmac_f32_dpp v183, v37, v197 row_shr:2 row_mask:0xf bank_mask:0xf
	v_fmac_f32_dpp v184, v38, v198 row_shr:2 row_mask:0xf bank_mask:0xf
	v_fmac_f32_dpp v185, v39, v199 row_shr:2 row_mask:0xf bank_mask:0xf
	v_fmac_f32_dpp v186, v32, v212 row_shr:2 row_mask:0xf bank_mask:0xf
	v_fmac_f32_dpp v187, v33, v213 row_shr:2 row_mask:0xf bank_mask:0xf
	v_fmac_f32_dpp v188, v34, v214 row_shr:2 row_mask:0xf bank_mask:0xf
	v_fmac_f32_dpp v189, v35, v215 row_shr:2 row_mask:0xf bank_mask:0xf
	v_fmac_f32_dpp v182, v44, v166 row_ror:1 row_mask:0xf bank_mask:0xf
	v_fmac_f32_dpp v183, v45, v167 row_ror:1 row_mask:0xf bank_mask:0xf
	v_fmac_f32_dpp v184, v46, v168 row_ror:1 row_mask:0xf bank_mask:0xf
	v_fmac_f32_dpp v185, v47, v169 row_ror:1 row_mask:0xf bank_mask:0xf
	v_fmac_f32_dpp v186, v40, v174 row_ror:1 row_mask:0xf bank_mask:0xf
	v_fmac_f32_dpp v187, v41, v175 row_ror:1 row_mask:0xf bank_mask:0xf
	v_fmac_f32_dpp v188, v42, v176 row_ror:1 row_mask:0xf bank_mask:0xf
	v_fmac_f32_dpp v189, v43, v177 row_ror:1 row_mask:0xf bank_mask:0xf
	v_fmac_f32_dpp v182, v44, v170 row_ror:2 row_mask:0xf bank_mask:0xf
	v_fmac_f32_dpp v183, v45, v171 row_ror:2 row_mask:0xf bank_mask:0xf
	v_fmac_f32_dpp v184, v46, v172 row_ror:2 row_mask:0xf bank_mask:0xf
	v_fmac_f32_dpp v185, v47, v173 row_ror:2 row_mask:0xf bank_mask:0xf
	v_fmac_f32_dpp v186, v40, v178 row_ror:2 row_mask:0xf bank_mask:0xf
	v_fmac_f32_dpp v187, v41, v179 row_ror:2 row_mask:0xf bank_mask:0xf
	v_fmac_f32_dpp v188, v42, v180 row_ror:2 row_mask:0xf bank_mask:0xf
	v_fmac_f32_dpp v189, v43, v181 row_ror:2 row_mask:0xf bank_mask:0xf
	v_pk_mul_f32 v[116:117], v[182:183], v[228:229]
	v_pk_mul_f32 v[118:119], v[184:185], v[228:229]
	v_exp_f32_e32 v116, v116
	v_exp_f32_e32 v117, v117
	v_exp_f32_e32 v118, v118
	v_exp_f32_e32 v119, v119
	v_pk_add_f32 v[116:117], v[116:117], v[230:231]
	v_pk_add_f32 v[118:119], v[118:119], v[230:231]
	v_rcp_f32_e32 v116, v116
	v_rcp_f32_e32 v117, v117
	v_rcp_f32_e32 v118, v118
	v_rcp_f32_e32 v119, v119
	v_pk_mul_f32 v[116:117], v[182:183], v[116:117]
	v_pk_mul_f32 v[118:119], v[184:185], v[118:119]
	v_pk_mul_f32 v[116:117], v[116:117], v[186:187]
	v_pk_mul_f32 v[118:119], v[118:119], v[188:189]
	v_cvt_pk_bf16_f32 v102, v116, v117
	v_cvt_pk_bf16_f32 v103, v118, v119
	v_add_u32_e32 v132, 0x42000, v129
	global_store_dwordx4 v132, v[100:103], s[48:49]
	v_pk_fma_f32 v[182:183], v[204:205], v[44:45], v[208:209]
	v_pk_fma_f32 v[184:185], v[206:207], v[46:47], v[210:211]
	v_pk_fma_f32 v[186:187], v[220:221], v[40:41], v[224:225]
	v_pk_fma_f32 v[188:189], v[222:223], v[42:43], v[226:227]
	v_fmac_f32_dpp v182, v44, v200 row_shr:1 row_mask:0xf bank_mask:0xf
	v_fmac_f32_dpp v183, v45, v201 row_shr:1 row_mask:0xf bank_mask:0xf
	v_fmac_f32_dpp v184, v46, v202 row_shr:1 row_mask:0xf bank_mask:0xf
	v_fmac_f32_dpp v185, v47, v203 row_shr:1 row_mask:0xf bank_mask:0xf
	v_fmac_f32_dpp v186, v40, v216 row_shr:1 row_mask:0xf bank_mask:0xf
	v_fmac_f32_dpp v187, v41, v217 row_shr:1 row_mask:0xf bank_mask:0xf
	v_fmac_f32_dpp v188, v42, v218 row_shr:1 row_mask:0xf bank_mask:0xf
	v_fmac_f32_dpp v189, v43, v219 row_shr:1 row_mask:0xf bank_mask:0xf
	v_fmac_f32_dpp v182, v44, v196 row_shr:2 row_mask:0xf bank_mask:0xf
	v_fmac_f32_dpp v183, v45, v197 row_shr:2 row_mask:0xf bank_mask:0xf
	v_fmac_f32_dpp v184, v46, v198 row_shr:2 row_mask:0xf bank_mask:0xf
	v_fmac_f32_dpp v185, v47, v199 row_shr:2 row_mask:0xf bank_mask:0xf
	v_fmac_f32_dpp v186, v40, v212 row_shr:2 row_mask:0xf bank_mask:0xf
	v_fmac_f32_dpp v187, v41, v213 row_shr:2 row_mask:0xf bank_mask:0xf
	v_fmac_f32_dpp v188, v42, v214 row_shr:2 row_mask:0xf bank_mask:0xf
	v_fmac_f32_dpp v189, v43, v215 row_shr:2 row_mask:0xf bank_mask:0xf
	v_fmac_f32_dpp v182, v52, v166 row_ror:1 row_mask:0xf bank_mask:0xf
	v_fmac_f32_dpp v183, v53, v167 row_ror:1 row_mask:0xf bank_mask:0xf
	v_fmac_f32_dpp v184, v54, v168 row_ror:1 row_mask:0xf bank_mask:0xf
	v_fmac_f32_dpp v185, v55, v169 row_ror:1 row_mask:0xf bank_mask:0xf
	v_fmac_f32_dpp v186, v48, v174 row_ror:1 row_mask:0xf bank_mask:0xf
	v_fmac_f32_dpp v187, v49, v175 row_ror:1 row_mask:0xf bank_mask:0xf
	v_fmac_f32_dpp v188, v50, v176 row_ror:1 row_mask:0xf bank_mask:0xf
	v_fmac_f32_dpp v189, v51, v177 row_ror:1 row_mask:0xf bank_mask:0xf
	v_fmac_f32_dpp v182, v52, v170 row_ror:2 row_mask:0xf bank_mask:0xf
	v_fmac_f32_dpp v183, v53, v171 row_ror:2 row_mask:0xf bank_mask:0xf
	v_fmac_f32_dpp v184, v54, v172 row_ror:2 row_mask:0xf bank_mask:0xf
	v_fmac_f32_dpp v185, v55, v173 row_ror:2 row_mask:0xf bank_mask:0xf
	v_fmac_f32_dpp v186, v48, v178 row_ror:2 row_mask:0xf bank_mask:0xf
	v_fmac_f32_dpp v187, v49, v179 row_ror:2 row_mask:0xf bank_mask:0xf
	v_fmac_f32_dpp v188, v50, v180 row_ror:2 row_mask:0xf bank_mask:0xf
	v_fmac_f32_dpp v189, v51, v181 row_ror:2 row_mask:0xf bank_mask:0xf
	v_pk_mul_f32 v[116:117], v[182:183], v[228:229]
	v_pk_mul_f32 v[118:119], v[184:185], v[228:229]
	v_exp_f32_e32 v116, v116
	v_exp_f32_e32 v117, v117
	v_exp_f32_e32 v118, v118
	v_exp_f32_e32 v119, v119
	v_pk_add_f32 v[116:117], v[116:117], v[230:231]
	v_pk_add_f32 v[118:119], v[118:119], v[230:231]
	v_rcp_f32_e32 v116, v116
	v_rcp_f32_e32 v117, v117
	v_rcp_f32_e32 v118, v118
	v_rcp_f32_e32 v119, v119
	v_pk_mul_f32 v[116:117], v[182:183], v[116:117]
	v_pk_mul_f32 v[118:119], v[184:185], v[118:119]
	v_pk_mul_f32 v[116:117], v[116:117], v[186:187]
	v_pk_mul_f32 v[118:119], v[118:119], v[188:189]
	v_cvt_pk_bf16_f32 v114, v116, v117
	v_cvt_pk_bf16_f32 v115, v118, v119
	v_add_u32_e32 v132, 0x2c000, v129
	global_store_dwordx4 v132, v[112:115], s[48:49]
	v_pk_fma_f32 v[182:183], v[204:205], v[52:53], v[208:209]
	v_pk_fma_f32 v[184:185], v[206:207], v[54:55], v[210:211]
	v_pk_fma_f32 v[186:187], v[220:221], v[48:49], v[224:225]
	v_pk_fma_f32 v[188:189], v[222:223], v[50:51], v[226:227]
	v_fmac_f32_dpp v182, v52, v200 row_shr:1 row_mask:0xf bank_mask:0xf
	v_fmac_f32_dpp v183, v53, v201 row_shr:1 row_mask:0xf bank_mask:0xf
	v_fmac_f32_dpp v184, v54, v202 row_shr:1 row_mask:0xf bank_mask:0xf
	v_fmac_f32_dpp v185, v55, v203 row_shr:1 row_mask:0xf bank_mask:0xf
	v_fmac_f32_dpp v186, v48, v216 row_shr:1 row_mask:0xf bank_mask:0xf
	v_fmac_f32_dpp v187, v49, v217 row_shr:1 row_mask:0xf bank_mask:0xf
	v_fmac_f32_dpp v188, v50, v218 row_shr:1 row_mask:0xf bank_mask:0xf
	v_fmac_f32_dpp v189, v51, v219 row_shr:1 row_mask:0xf bank_mask:0xf
	v_fmac_f32_dpp v182, v52, v196 row_shr:2 row_mask:0xf bank_mask:0xf
	v_fmac_f32_dpp v183, v53, v197 row_shr:2 row_mask:0xf bank_mask:0xf
	v_fmac_f32_dpp v184, v54, v198 row_shr:2 row_mask:0xf bank_mask:0xf
	v_fmac_f32_dpp v185, v55, v199 row_shr:2 row_mask:0xf bank_mask:0xf
	v_fmac_f32_dpp v186, v48, v212 row_shr:2 row_mask:0xf bank_mask:0xf
	v_fmac_f32_dpp v187, v49, v213 row_shr:2 row_mask:0xf bank_mask:0xf
	v_fmac_f32_dpp v188, v50, v214 row_shr:2 row_mask:0xf bank_mask:0xf
	v_fmac_f32_dpp v189, v51, v215 row_shr:2 row_mask:0xf bank_mask:0xf
	v_fmac_f32_dpp v182, v60, v166 row_ror:1 row_mask:0xf bank_mask:0xf
	v_fmac_f32_dpp v183, v61, v167 row_ror:1 row_mask:0xf bank_mask:0xf
	v_fmac_f32_dpp v184, v62, v168 row_ror:1 row_mask:0xf bank_mask:0xf
	v_fmac_f32_dpp v185, v63, v169 row_ror:1 row_mask:0xf bank_mask:0xf
	v_fmac_f32_dpp v186, v56, v174 row_ror:1 row_mask:0xf bank_mask:0xf
	v_fmac_f32_dpp v187, v57, v175 row_ror:1 row_mask:0xf bank_mask:0xf
	v_fmac_f32_dpp v188, v58, v176 row_ror:1 row_mask:0xf bank_mask:0xf
	v_fmac_f32_dpp v189, v59, v177 row_ror:1 row_mask:0xf bank_mask:0xf
	v_fmac_f32_dpp v182, v60, v170 row_ror:2 row_mask:0xf bank_mask:0xf
	v_fmac_f32_dpp v183, v61, v171 row_ror:2 row_mask:0xf bank_mask:0xf
	v_fmac_f32_dpp v184, v62, v172 row_ror:2 row_mask:0xf bank_mask:0xf
	v_fmac_f32_dpp v185, v63, v173 row_ror:2 row_mask:0xf bank_mask:0xf
	v_fmac_f32_dpp v186, v56, v178 row_ror:2 row_mask:0xf bank_mask:0xf
	v_fmac_f32_dpp v187, v57, v179 row_ror:2 row_mask:0xf bank_mask:0xf
	v_fmac_f32_dpp v188, v58, v180 row_ror:2 row_mask:0xf bank_mask:0xf
	v_fmac_f32_dpp v189, v59, v181 row_ror:2 row_mask:0xf bank_mask:0xf
	v_pk_mul_f32 v[116:117], v[182:183], v[228:229]
	v_pk_mul_f32 v[118:119], v[184:185], v[228:229]
	v_exp_f32_e32 v116, v116
	v_exp_f32_e32 v117, v117
	v_exp_f32_e32 v118, v118
	v_exp_f32_e32 v119, v119
	v_pk_add_f32 v[116:117], v[116:117], v[230:231]
	v_pk_add_f32 v[118:119], v[118:119], v[230:231]
	v_rcp_f32_e32 v116, v116
	v_rcp_f32_e32 v117, v117
	v_rcp_f32_e32 v118, v118
	v_rcp_f32_e32 v119, v119
	v_pk_mul_f32 v[116:117], v[182:183], v[116:117]
	v_pk_mul_f32 v[118:119], v[184:185], v[118:119]
	v_pk_mul_f32 v[116:117], v[116:117], v[186:187]
	v_pk_mul_f32 v[118:119], v[118:119], v[188:189]
	v_cvt_pk_bf16_f32 v140, v116, v117
	v_cvt_pk_bf16_f32 v141, v118, v119
	v_add_u32_e32 v132, 0x16000, v129
	global_store_dwordx4 v132, v[138:141], s[48:49]
	v_pk_fma_f32 v[182:183], v[204:205], v[60:61], v[208:209]
	v_pk_fma_f32 v[184:185], v[206:207], v[62:63], v[210:211]
	v_pk_fma_f32 v[186:187], v[220:221], v[56:57], v[224:225]
	v_pk_fma_f32 v[188:189], v[222:223], v[58:59], v[226:227]
	v_fmac_f32_dpp v182, v60, v200 row_shr:1 row_mask:0xf bank_mask:0xf
	v_fmac_f32_dpp v183, v61, v201 row_shr:1 row_mask:0xf bank_mask:0xf
	v_fmac_f32_dpp v184, v62, v202 row_shr:1 row_mask:0xf bank_mask:0xf
	v_fmac_f32_dpp v185, v63, v203 row_shr:1 row_mask:0xf bank_mask:0xf
	v_fmac_f32_dpp v186, v56, v216 row_shr:1 row_mask:0xf bank_mask:0xf
	v_fmac_f32_dpp v187, v57, v217 row_shr:1 row_mask:0xf bank_mask:0xf
	v_fmac_f32_dpp v188, v58, v218 row_shr:1 row_mask:0xf bank_mask:0xf
	v_fmac_f32_dpp v189, v59, v219 row_shr:1 row_mask:0xf bank_mask:0xf
	v_fmac_f32_dpp v182, v60, v196 row_shr:2 row_mask:0xf bank_mask:0xf
	v_fmac_f32_dpp v183, v61, v197 row_shr:2 row_mask:0xf bank_mask:0xf
	v_fmac_f32_dpp v184, v62, v198 row_shr:2 row_mask:0xf bank_mask:0xf
	v_fmac_f32_dpp v185, v63, v199 row_shr:2 row_mask:0xf bank_mask:0xf
	v_fmac_f32_dpp v186, v56, v212 row_shr:2 row_mask:0xf bank_mask:0xf
	v_fmac_f32_dpp v187, v57, v213 row_shr:2 row_mask:0xf bank_mask:0xf
	v_fmac_f32_dpp v188, v58, v214 row_shr:2 row_mask:0xf bank_mask:0xf
	v_fmac_f32_dpp v189, v59, v215 row_shr:2 row_mask:0xf bank_mask:0xf
	v_pk_mul_f32 v[116:117], v[182:183], v[228:229]
	v_pk_mul_f32 v[118:119], v[184:185], v[228:229]
	v_exp_f32_e32 v116, v116
	v_exp_f32_e32 v117, v117
	v_exp_f32_e32 v118, v118
	v_exp_f32_e32 v119, v119
	v_pk_add_f32 v[116:117], v[116:117], v[230:231]
	v_pk_add_f32 v[118:119], v[118:119], v[230:231]
	v_rcp_f32_e32 v116, v116
	v_rcp_f32_e32 v117, v117
	v_rcp_f32_e32 v118, v118
	v_rcp_f32_e32 v119, v119
	v_pk_mul_f32 v[116:117], v[182:183], v[116:117]
	v_pk_mul_f32 v[118:119], v[184:185], v[118:119]
	v_pk_mul_f32 v[116:117], v[116:117], v[186:187]
	v_pk_mul_f32 v[118:119], v[118:119], v[188:189]
	v_cvt_pk_bf16_f32 v144, v116, v117
	v_cvt_pk_bf16_f32 v145, v118, v119
	s_mov_b64 exec, s[4:5]
	global_store_dwordx4 v129, v[142:145], s[48:49]
	s_mov_b64 exec, -1
	v_pk_fma_f32 v[182:183], v[204:205], v[4:5], v[208:209]
	v_pk_fma_f32 v[184:185], v[206:207], v[6:7], v[210:211]
	v_pk_fma_f32 v[186:187], v[220:221], v[0:1], v[224:225]
	v_pk_fma_f32 v[188:189], v[222:223], v[2:3], v[226:227]
	v_fmac_f32_dpp v182, v4, v200 row_shr:1 row_mask:0xf bank_mask:0xf
	v_fmac_f32_dpp v183, v5, v201 row_shr:1 row_mask:0xf bank_mask:0xf
	v_fmac_f32_dpp v184, v6, v202 row_shr:1 row_mask:0xf bank_mask:0xf
	v_fmac_f32_dpp v185, v7, v203 row_shr:1 row_mask:0xf bank_mask:0xf
	v_fmac_f32_dpp v186, v0, v216 row_shr:1 row_mask:0xf bank_mask:0xf
	v_fmac_f32_dpp v187, v1, v217 row_shr:1 row_mask:0xf bank_mask:0xf
	v_fmac_f32_dpp v188, v2, v218 row_shr:1 row_mask:0xf bank_mask:0xf
	v_fmac_f32_dpp v189, v3, v219 row_shr:1 row_mask:0xf bank_mask:0xf
	v_fmac_f32_dpp v182, v4, v196 row_shr:2 row_mask:0xf bank_mask:0xf
	v_fmac_f32_dpp v183, v5, v197 row_shr:2 row_mask:0xf bank_mask:0xf
	v_fmac_f32_dpp v184, v6, v198 row_shr:2 row_mask:0xf bank_mask:0xf
	v_fmac_f32_dpp v185, v7, v199 row_shr:2 row_mask:0xf bank_mask:0xf
	v_fmac_f32_dpp v186, v0, v212 row_shr:2 row_mask:0xf bank_mask:0xf
	v_fmac_f32_dpp v187, v1, v213 row_shr:2 row_mask:0xf bank_mask:0xf
	v_fmac_f32_dpp v188, v2, v214 row_shr:2 row_mask:0xf bank_mask:0xf
	v_fmac_f32_dpp v189, v3, v215 row_shr:2 row_mask:0xf bank_mask:0xf
	v_fmac_f32_dpp v182, v12, v166 row_ror:1 row_mask:0xf bank_mask:0xf
	v_fmac_f32_dpp v183, v13, v167 row_ror:1 row_mask:0xf bank_mask:0xf
	v_fmac_f32_dpp v184, v14, v168 row_ror:1 row_mask:0xf bank_mask:0xf
	v_fmac_f32_dpp v185, v15, v169 row_ror:1 row_mask:0xf bank_mask:0xf
	v_fmac_f32_dpp v186, v8, v174 row_ror:1 row_mask:0xf bank_mask:0xf
	v_fmac_f32_dpp v187, v9, v175 row_ror:1 row_mask:0xf bank_mask:0xf
	v_fmac_f32_dpp v188, v10, v176 row_ror:1 row_mask:0xf bank_mask:0xf
	v_fmac_f32_dpp v189, v11, v177 row_ror:1 row_mask:0xf bank_mask:0xf
	v_fmac_f32_dpp v182, v12, v170 row_ror:2 row_mask:0xf bank_mask:0xf
	v_fmac_f32_dpp v183, v13, v171 row_ror:2 row_mask:0xf bank_mask:0xf
	v_fmac_f32_dpp v184, v14, v172 row_ror:2 row_mask:0xf bank_mask:0xf
	v_fmac_f32_dpp v185, v15, v173 row_ror:2 row_mask:0xf bank_mask:0xf
	v_fmac_f32_dpp v186, v8, v178 row_ror:2 row_mask:0xf bank_mask:0xf
	v_fmac_f32_dpp v187, v9, v179 row_ror:2 row_mask:0xf bank_mask:0xf
	v_fmac_f32_dpp v188, v10, v180 row_ror:2 row_mask:0xf bank_mask:0xf
	v_fmac_f32_dpp v189, v11, v181 row_ror:2 row_mask:0xf bank_mask:0xf
	v_pk_mul_f32 v[116:117], v[182:183], v[228:229]
	v_pk_mul_f32 v[118:119], v[184:185], v[228:229]
	v_exp_f32_e32 v116, v116
	v_exp_f32_e32 v117, v117
	v_exp_f32_e32 v118, v118
	v_exp_f32_e32 v119, v119
	v_pk_add_f32 v[116:117], v[116:117], v[230:231]
	v_pk_add_f32 v[118:119], v[118:119], v[230:231]
	v_rcp_f32_e32 v116, v116
	v_rcp_f32_e32 v117, v117
	v_rcp_f32_e32 v118, v118
	v_rcp_f32_e32 v119, v119
	v_pk_mul_f32 v[116:117], v[182:183], v[116:117]
	v_pk_mul_f32 v[118:119], v[184:185], v[118:119]
	v_pk_mul_f32 v[116:117], v[116:117], v[186:187]
	v_pk_mul_f32 v[118:119], v[118:119], v[188:189]
	v_cvt_pk_bf16_f32 v70, v116, v117
	v_cvt_pk_bf16_f32 v71, v118, v119
	v_add_u32_e32 v132, 0xf2000, v129
	global_store_dwordx4 v132, v[68:71], s[48:49]
	v_pk_fma_f32 v[182:183], v[204:205], v[12:13], v[208:209]
	v_pk_fma_f32 v[184:185], v[206:207], v[14:15], v[210:211]
	v_pk_fma_f32 v[186:187], v[220:221], v[8:9], v[224:225]
	v_pk_fma_f32 v[188:189], v[222:223], v[10:11], v[226:227]
	v_fmac_f32_dpp v182, v12, v200 row_shr:1 row_mask:0xf bank_mask:0xf
	v_fmac_f32_dpp v183, v13, v201 row_shr:1 row_mask:0xf bank_mask:0xf
	v_fmac_f32_dpp v184, v14, v202 row_shr:1 row_mask:0xf bank_mask:0xf
	v_fmac_f32_dpp v185, v15, v203 row_shr:1 row_mask:0xf bank_mask:0xf
	v_fmac_f32_dpp v186, v8, v216 row_shr:1 row_mask:0xf bank_mask:0xf
	v_fmac_f32_dpp v187, v9, v217 row_shr:1 row_mask:0xf bank_mask:0xf
	v_fmac_f32_dpp v188, v10, v218 row_shr:1 row_mask:0xf bank_mask:0xf
	v_fmac_f32_dpp v189, v11, v219 row_shr:1 row_mask:0xf bank_mask:0xf
	v_fmac_f32_dpp v182, v12, v196 row_shr:2 row_mask:0xf bank_mask:0xf
	v_fmac_f32_dpp v183, v13, v197 row_shr:2 row_mask:0xf bank_mask:0xf
	v_fmac_f32_dpp v184, v14, v198 row_shr:2 row_mask:0xf bank_mask:0xf
	v_fmac_f32_dpp v185, v15, v199 row_shr:2 row_mask:0xf bank_mask:0xf
	v_fmac_f32_dpp v186, v8, v212 row_shr:2 row_mask:0xf bank_mask:0xf
	v_fmac_f32_dpp v187, v9, v213 row_shr:2 row_mask:0xf bank_mask:0xf
	v_fmac_f32_dpp v188, v10, v214 row_shr:2 row_mask:0xf bank_mask:0xf
	v_fmac_f32_dpp v189, v11, v215 row_shr:2 row_mask:0xf bank_mask:0xf
	v_fmac_f32_dpp v182, v20, v166 row_ror:1 row_mask:0xf bank_mask:0xf
	v_fmac_f32_dpp v183, v21, v167 row_ror:1 row_mask:0xf bank_mask:0xf
	v_fmac_f32_dpp v184, v22, v168 row_ror:1 row_mask:0xf bank_mask:0xf
	v_fmac_f32_dpp v185, v23, v169 row_ror:1 row_mask:0xf bank_mask:0xf
	v_fmac_f32_dpp v186, v16, v174 row_ror:1 row_mask:0xf bank_mask:0xf
	v_fmac_f32_dpp v187, v17, v175 row_ror:1 row_mask:0xf bank_mask:0xf
	v_fmac_f32_dpp v188, v18, v176 row_ror:1 row_mask:0xf bank_mask:0xf
	v_fmac_f32_dpp v189, v19, v177 row_ror:1 row_mask:0xf bank_mask:0xf
	v_fmac_f32_dpp v182, v20, v170 row_ror:2 row_mask:0xf bank_mask:0xf
	v_fmac_f32_dpp v183, v21, v171 row_ror:2 row_mask:0xf bank_mask:0xf
	v_fmac_f32_dpp v184, v22, v172 row_ror:2 row_mask:0xf bank_mask:0xf
	v_fmac_f32_dpp v185, v23, v173 row_ror:2 row_mask:0xf bank_mask:0xf
	v_fmac_f32_dpp v186, v16, v178 row_ror:2 row_mask:0xf bank_mask:0xf
	v_fmac_f32_dpp v187, v17, v179 row_ror:2 row_mask:0xf bank_mask:0xf
	v_fmac_f32_dpp v188, v18, v180 row_ror:2 row_mask:0xf bank_mask:0xf
	v_fmac_f32_dpp v189, v19, v181 row_ror:2 row_mask:0xf bank_mask:0xf
	v_pk_mul_f32 v[116:117], v[182:183], v[228:229]
	v_pk_mul_f32 v[118:119], v[184:185], v[228:229]
	v_exp_f32_e32 v116, v116
	v_exp_f32_e32 v117, v117
	v_exp_f32_e32 v118, v118
	v_exp_f32_e32 v119, v119
	v_pk_add_f32 v[116:117], v[116:117], v[230:231]
	v_pk_add_f32 v[118:119], v[118:119], v[230:231]
	v_rcp_f32_e32 v116, v116
	v_rcp_f32_e32 v117, v117
	v_rcp_f32_e32 v118, v118
	v_rcp_f32_e32 v119, v119
	v_pk_mul_f32 v[116:117], v[182:183], v[116:117]
	v_pk_mul_f32 v[118:119], v[184:185], v[118:119]
	v_pk_mul_f32 v[116:117], v[116:117], v[186:187]
	v_pk_mul_f32 v[118:119], v[118:119], v[188:189]
	v_cvt_pk_bf16_f32 v78, v116, v117
	v_cvt_pk_bf16_f32 v79, v118, v119
	v_add_u32_e32 v132, 0xdc000, v129
	global_store_dwordx4 v132, v[76:79], s[48:49]
	v_pk_fma_f32 v[182:183], v[204:205], v[20:21], v[208:209]
	v_pk_fma_f32 v[184:185], v[206:207], v[22:23], v[210:211]
	v_pk_fma_f32 v[186:187], v[220:221], v[16:17], v[224:225]
	v_pk_fma_f32 v[188:189], v[222:223], v[18:19], v[226:227]
	v_fmac_f32_dpp v182, v20, v200 row_shr:1 row_mask:0xf bank_mask:0xf
	v_fmac_f32_dpp v183, v21, v201 row_shr:1 row_mask:0xf bank_mask:0xf
	v_fmac_f32_dpp v184, v22, v202 row_shr:1 row_mask:0xf bank_mask:0xf
	v_fmac_f32_dpp v185, v23, v203 row_shr:1 row_mask:0xf bank_mask:0xf
	v_fmac_f32_dpp v186, v16, v216 row_shr:1 row_mask:0xf bank_mask:0xf
	v_fmac_f32_dpp v187, v17, v217 row_shr:1 row_mask:0xf bank_mask:0xf
	v_fmac_f32_dpp v188, v18, v218 row_shr:1 row_mask:0xf bank_mask:0xf
	v_fmac_f32_dpp v189, v19, v219 row_shr:1 row_mask:0xf bank_mask:0xf
	v_fmac_f32_dpp v182, v20, v196 row_shr:2 row_mask:0xf bank_mask:0xf
	v_fmac_f32_dpp v183, v21, v197 row_shr:2 row_mask:0xf bank_mask:0xf
	v_fmac_f32_dpp v184, v22, v198 row_shr:2 row_mask:0xf bank_mask:0xf
	v_fmac_f32_dpp v185, v23, v199 row_shr:2 row_mask:0xf bank_mask:0xf
	v_fmac_f32_dpp v186, v16, v212 row_shr:2 row_mask:0xf bank_mask:0xf
	v_fmac_f32_dpp v187, v17, v213 row_shr:2 row_mask:0xf bank_mask:0xf
	v_fmac_f32_dpp v188, v18, v214 row_shr:2 row_mask:0xf bank_mask:0xf
	v_fmac_f32_dpp v189, v19, v215 row_shr:2 row_mask:0xf bank_mask:0xf
	v_fmac_f32_dpp v182, v28, v166 row_ror:1 row_mask:0xf bank_mask:0xf
	v_fmac_f32_dpp v183, v29, v167 row_ror:1 row_mask:0xf bank_mask:0xf
	v_fmac_f32_dpp v184, v30, v168 row_ror:1 row_mask:0xf bank_mask:0xf
	v_fmac_f32_dpp v185, v31, v169 row_ror:1 row_mask:0xf bank_mask:0xf
	v_fmac_f32_dpp v186, v24, v174 row_ror:1 row_mask:0xf bank_mask:0xf
	v_fmac_f32_dpp v187, v25, v175 row_ror:1 row_mask:0xf bank_mask:0xf
	v_fmac_f32_dpp v188, v26, v176 row_ror:1 row_mask:0xf bank_mask:0xf
	v_fmac_f32_dpp v189, v27, v177 row_ror:1 row_mask:0xf bank_mask:0xf
	v_fmac_f32_dpp v182, v28, v170 row_ror:2 row_mask:0xf bank_mask:0xf
	v_fmac_f32_dpp v183, v29, v171 row_ror:2 row_mask:0xf bank_mask:0xf
	v_fmac_f32_dpp v184, v30, v172 row_ror:2 row_mask:0xf bank_mask:0xf
	v_fmac_f32_dpp v185, v31, v173 row_ror:2 row_mask:0xf bank_mask:0xf
	v_fmac_f32_dpp v186, v24, v178 row_ror:2 row_mask:0xf bank_mask:0xf
	v_fmac_f32_dpp v187, v25, v179 row_ror:2 row_mask:0xf bank_mask:0xf
	v_fmac_f32_dpp v188, v26, v180 row_ror:2 row_mask:0xf bank_mask:0xf
	v_fmac_f32_dpp v189, v27, v181 row_ror:2 row_mask:0xf bank_mask:0xf
	v_pk_mul_f32 v[116:117], v[182:183], v[228:229]
	v_pk_mul_f32 v[118:119], v[184:185], v[228:229]
	v_exp_f32_e32 v116, v116
	v_exp_f32_e32 v117, v117
	v_exp_f32_e32 v118, v118
	v_exp_f32_e32 v119, v119
	v_pk_add_f32 v[116:117], v[116:117], v[230:231]
	v_pk_add_f32 v[118:119], v[118:119], v[230:231]
	v_rcp_f32_e32 v116, v116
	v_rcp_f32_e32 v117, v117
	v_rcp_f32_e32 v118, v118
	v_rcp_f32_e32 v119, v119
	v_pk_mul_f32 v[116:117], v[182:183], v[116:117]
	v_pk_mul_f32 v[118:119], v[184:185], v[118:119]
	v_pk_mul_f32 v[116:117], v[116:117], v[186:187]
	v_pk_mul_f32 v[118:119], v[118:119], v[188:189]
	v_cvt_pk_bf16_f32 v86, v116, v117
	v_cvt_pk_bf16_f32 v87, v118, v119
	v_add_u32_e32 v132, 0xc6000, v129
	global_store_dwordx4 v132, v[84:87], s[48:49]
	v_pk_fma_f32 v[182:183], v[204:205], v[28:29], v[208:209]
	v_pk_fma_f32 v[184:185], v[206:207], v[30:31], v[210:211]
	v_pk_fma_f32 v[186:187], v[220:221], v[24:25], v[224:225]
	v_pk_fma_f32 v[188:189], v[222:223], v[26:27], v[226:227]
	v_fmac_f32_dpp v182, v28, v200 row_shr:1 row_mask:0xf bank_mask:0xf
	v_fmac_f32_dpp v183, v29, v201 row_shr:1 row_mask:0xf bank_mask:0xf
	v_fmac_f32_dpp v184, v30, v202 row_shr:1 row_mask:0xf bank_mask:0xf
	v_fmac_f32_dpp v185, v31, v203 row_shr:1 row_mask:0xf bank_mask:0xf
	v_fmac_f32_dpp v186, v24, v216 row_shr:1 row_mask:0xf bank_mask:0xf
	v_fmac_f32_dpp v187, v25, v217 row_shr:1 row_mask:0xf bank_mask:0xf
	v_fmac_f32_dpp v188, v26, v218 row_shr:1 row_mask:0xf bank_mask:0xf
	v_fmac_f32_dpp v189, v27, v219 row_shr:1 row_mask:0xf bank_mask:0xf
	v_fmac_f32_dpp v182, v28, v196 row_shr:2 row_mask:0xf bank_mask:0xf
	v_fmac_f32_dpp v183, v29, v197 row_shr:2 row_mask:0xf bank_mask:0xf
	v_fmac_f32_dpp v184, v30, v198 row_shr:2 row_mask:0xf bank_mask:0xf
	v_fmac_f32_dpp v185, v31, v199 row_shr:2 row_mask:0xf bank_mask:0xf
	v_fmac_f32_dpp v186, v24, v212 row_shr:2 row_mask:0xf bank_mask:0xf
	v_fmac_f32_dpp v187, v25, v213 row_shr:2 row_mask:0xf bank_mask:0xf
	v_fmac_f32_dpp v188, v26, v214 row_shr:2 row_mask:0xf bank_mask:0xf
	v_fmac_f32_dpp v189, v27, v215 row_shr:2 row_mask:0xf bank_mask:0xf
	v_pk_mul_f32 v[116:117], v[182:183], v[228:229]
	v_pk_mul_f32 v[118:119], v[184:185], v[228:229]
	v_exp_f32_e32 v116, v116
	v_exp_f32_e32 v117, v117
	v_exp_f32_e32 v118, v118
	v_exp_f32_e32 v119, v119
	v_pk_add_f32 v[116:117], v[116:117], v[230:231]
	v_pk_add_f32 v[118:119], v[118:119], v[230:231]
	v_rcp_f32_e32 v116, v116
	v_rcp_f32_e32 v117, v117
	v_rcp_f32_e32 v118, v118
	v_rcp_f32_e32 v119, v119
	v_pk_mul_f32 v[116:117], v[182:183], v[116:117]
	v_pk_mul_f32 v[118:119], v[184:185], v[118:119]
	v_pk_mul_f32 v[116:117], v[116:117], v[186:187]
	v_pk_mul_f32 v[118:119], v[118:119], v[188:189]
	v_cvt_pk_bf16_f32 v94, v116, v117
	v_cvt_pk_bf16_f32 v95, v118, v119
	v_add_u32_e32 v132, 0xb0000, v129
	s_mov_b64 exec, s[4:5]
	global_store_dwordx4 v132, v[92:95], s[48:49]
	s_mov_b64 exec, -1

.LBB0_1265:
	s_add_i32 m0, s68, 0x18000
	v_lshl_add_u64 v[0:1], v[0:1], 0, s[22:23]
	s_and_b32 s60, s27, 3
	s_lshl_b32 s70, s59, 6
	s_lshl_b32 s8, s59, 13
	s_waitcnt vmcnt(2)
	s_barrier
	global_load_lds_dwordx4 v[0:1], off
	v_lshl_add_u64 v[0:1], v[2:3], 0, s[22:23]
	s_add_i32 m0, s68, 0x1a000
	s_add_i32 s73, s68, 0x8000
	s_add_i32 s74, s68, 0xa000
	v_bitop3_b32 v8, v185, s8, v186 bitop3:0xde
	global_load_lds_dwordx4 v[0:1], off
	v_lshl_add_u64 v[0:1], v[6:7], 0, s[22:23]
	s_mov_b32 m0, s73
	s_add_u32 s8, s38, 0xb0080
	global_load_lds_dwordx4 v[0:1], off
	v_lshl_add_u64 v[0:1], v[4:5], 0, s[22:23]
	s_mov_b32 m0, s74
	s_addc_u32 s9, s39, 0
	global_load_lds_dwordx4 v[0:1], off
	s_add_i32 m0, s68, 0x1c000
	v_lshl_add_u64 v[0:1], s[8:9], 0, v[164:165]
	global_load_lds_dwordx4 v[0:1], off
	v_lshl_add_u64 v[0:1], s[8:9], 0, v[168:169]
	s_add_i32 m0, s68, 0x1e000
	v_or_b32_e32 v179, s70, v181
	global_load_lds_dwordx4 v[0:1], off
	s_waitcnt vmcnt(6)
	v_mov_b32_e32 v0, 0
	v_lshl_or_b32 v132, s60, 12, v182
	s_mov_b32 s75, 0
	v_add_u32_e32 v133, 0, v8
	v_mov_b32_e32 v1, 0
	v_mov_b64_e32 v[2:3], 0
	v_mov_b64_e32 v[4:5], 0
	v_mov_b64_e32 v[6:7], 0
	v_mov_b64_e32 v[16:17], 0
	v_mov_b64_e32 v[18:19], 0
	v_mov_b64_e32 v[20:21], 0
	v_mov_b64_e32 v[22:23], 0
	v_mov_b64_e32 v[32:33], 0
	v_mov_b64_e32 v[34:35], 0
	v_mov_b64_e32 v[36:37], 0
	v_mov_b64_e32 v[38:39], 0
	v_mov_b64_e32 v[48:49], 0
	v_mov_b64_e32 v[50:51], 0
	v_mov_b64_e32 v[52:53], 0
	v_mov_b64_e32 v[54:55], 0
	v_mov_b64_e32 v[8:9], 0
	v_mov_b64_e32 v[10:11], 0
	v_mov_b64_e32 v[12:13], 0
	v_mov_b64_e32 v[14:15], 0
	v_mov_b64_e32 v[24:25], 0
	v_mov_b64_e32 v[26:27], 0
	v_mov_b64_e32 v[28:29], 0
	v_mov_b64_e32 v[30:31], 0
	v_mov_b64_e32 v[40:41], 0
	v_mov_b64_e32 v[42:43], 0
	v_mov_b64_e32 v[44:45], 0
	v_mov_b64_e32 v[46:47], 0
	v_mov_b64_e32 v[56:57], 0
	v_mov_b64_e32 v[58:59], 0
	v_mov_b64_e32 v[60:61], 0
	v_mov_b64_e32 v[62:63], 0
	v_mov_b64_e32 v[68:69], 0
	v_mov_b64_e32 v[70:71], 0
	v_mov_b64_e32 v[84:85], 0
	v_mov_b64_e32 v[86:87], 0
	v_mov_b64_e32 v[96:97], 0
	v_mov_b64_e32 v[98:99], 0
	v_mov_b64_e32 v[100:101], 0
	v_mov_b64_e32 v[102:103], 0
	v_mov_b64_e32 v[88:89], 0
	v_mov_b64_e32 v[90:91], 0
	v_mov_b64_e32 v[92:93], 0
	v_mov_b64_e32 v[94:95], 0
	v_mov_b64_e32 v[64:65], 0
	v_mov_b64_e32 v[66:67], 0
	v_mov_b64_e32 v[72:73], 0
	v_mov_b64_e32 v[74:75], 0
	v_mov_b64_e32 v[112:113], 0
	v_mov_b64_e32 v[114:115], 0
	v_mov_b64_e32 v[120:121], 0
	v_mov_b64_e32 v[122:123], 0
	v_mov_b64_e32 v[108:109], 0
	v_mov_b64_e32 v[110:111], 0
	v_mov_b64_e32 v[116:117], 0
	v_mov_b64_e32 v[118:119], 0
	v_mov_b64_e32 v[104:105], 0
	v_mov_b64_e32 v[106:107], 0
	v_mov_b64_e32 v[124:125], 0
	v_mov_b64_e32 v[126:127], 0
	v_mov_b64_e32 v[76:77], 0
	v_mov_b64_e32 v[78:79], 0
	v_mov_b64_e32 v[80:81], 0
	v_mov_b64_e32 v[82:83], 0
	s_barrier
	s_add_i32 s78, s75, 1
	s_cmp_ge_i32 s78, s62
	s_mov_b64 s[34:35], 0
	s_cbranch_scc1 .LBB0_1272

.LBB0_1277:
	s_add_u32 s40, s28, s38
	s_addc_u32 s41, s29, s39
	s_add_u32 s40, s40, 0x100
	s_addc_u32 s41, s41, 0
	s_add_u32 s82, s79, s38
	s_addc_u32 s83, s80, s39
	s_add_i32 s84, 0, 0x10000
	s_cmpk_eq_i32 s38, 0x1500
	s_cselect_b32 s43, s37, s41
	s_cselect_b32 s42, s36, s40
	s_cselect_b32 s41, s35, s83
	s_cselect_b32 s40, s34, s82
	s_add_i32 s85, 0, 0x14000
	v_add_u32_e32 v146, s84, v132
	v_add_u32_e32 v158, s85, v132
	ds_read_b128 v[134:137], v146
	ds_read_b128 v[138:141], v146 offset:1024
	ds_read_b128 v[142:145], v146 offset:2048
	ds_read_b128 v[146:149], v146 offset:3072
	ds_read_b128 v[150:153], v158
	ds_read_b128 v[154:157], v158 offset:1024
	ds_read_b128 v[194:197], v158 offset:2048
	ds_read_b128 v[198:201], v158 offset:3072
	v_lshl_add_u64 v[158:159], v[128:129], 0, s[38:39]
	s_add_i32 m0, s68, 0xc000
	ds_read_b128 v[202:205], v133
	ds_read_b128 v[206:209], v133 offset:1024
	ds_read_b128 v[210:213], v133 offset:2048
	ds_read_b128 v[214:217], v133 offset:3072
	ds_read_b128 v[218:221], v133 offset:4096
	ds_read_b128 v[222:225], v133 offset:5120
	ds_read_b128 v[226:229], v133 offset:6144
	ds_read_b128 v[230:233], v133 offset:7168
	global_load_lds_dwordx4 v[158:159], off
	v_lshl_add_u64 v[158:159], v[130:131], 0, s[38:39]
	s_add_i32 m0, s68, 0xe000
	s_nop 0
	global_load_lds_dwordx4 v[158:159], off
	s_waitcnt vmcnt(8)
	s_waitcnt lgkmcnt(0)
	s_barrier
	s_setprio 1
	s_waitcnt lgkmcnt(0)
	v_mfma_f32_16x16x32_bf16 v[80:83], v[134:137], v[202:205], v[80:83]
	v_mfma_f32_16x16x32_bf16 v[76:79], v[142:145], v[202:205], v[76:79]
	v_mfma_f32_16x16x32_bf16 v[124:127], v[134:137], v[210:213], v[124:127]
	v_mfma_f32_16x16x32_bf16 v[104:107], v[142:145], v[210:213], v[104:107]
	v_mfma_f32_16x16x32_bf16 v[116:119], v[134:137], v[218:221], v[116:119]
	v_mfma_f32_16x16x32_bf16 v[108:111], v[142:145], v[218:221], v[108:111]
	v_mfma_f32_16x16x32_bf16 v[120:123], v[134:137], v[226:229], v[120:123]
	v_mfma_f32_16x16x32_bf16 v[112:115], v[142:145], v[226:229], v[112:115]
	v_mfma_f32_16x16x32_bf16 v[80:83], v[138:141], v[206:209], v[80:83]
	v_mfma_f32_16x16x32_bf16 v[76:79], v[146:149], v[206:209], v[76:79]
	v_mfma_f32_16x16x32_bf16 v[124:127], v[138:141], v[214:217], v[124:127]
	v_mfma_f32_16x16x32_bf16 v[104:107], v[146:149], v[214:217], v[104:107]
	v_mfma_f32_16x16x32_bf16 v[116:119], v[138:141], v[222:225], v[116:119]
	v_mfma_f32_16x16x32_bf16 v[108:111], v[146:149], v[222:225], v[108:111]
	v_mfma_f32_16x16x32_bf16 v[120:123], v[138:141], v[230:233], v[120:123]
	v_mfma_f32_16x16x32_bf16 v[112:115], v[146:149], v[230:233], v[112:115]
	s_setprio 0
	s_setprio 1
	v_mfma_f32_16x16x32_bf16 v[72:75], v[150:153], v[202:205], v[72:75]
	v_mfma_f32_16x16x32_bf16 v[64:67], v[194:197], v[202:205], v[64:67]
	v_mfma_f32_16x16x32_bf16 v[92:95], v[150:153], v[210:213], v[92:95]
	v_mfma_f32_16x16x32_bf16 v[88:91], v[194:197], v[210:213], v[88:91]
	v_mfma_f32_16x16x32_bf16 v[100:103], v[150:153], v[218:221], v[100:103]
	v_mfma_f32_16x16x32_bf16 v[96:99], v[194:197], v[218:221], v[96:99]
	v_mfma_f32_16x16x32_bf16 v[84:87], v[150:153], v[226:229], v[84:87]
	v_mfma_f32_16x16x32_bf16 v[68:71], v[194:197], v[226:229], v[68:71]
	v_mfma_f32_16x16x32_bf16 v[72:75], v[154:157], v[206:209], v[72:75]
	v_mfma_f32_16x16x32_bf16 v[64:67], v[198:201], v[206:209], v[64:67]
	v_mfma_f32_16x16x32_bf16 v[92:95], v[154:157], v[214:217], v[92:95]
	v_mfma_f32_16x16x32_bf16 v[88:91], v[198:201], v[214:217], v[88:91]
	v_mfma_f32_16x16x32_bf16 v[100:103], v[154:157], v[222:225], v[100:103]
	v_mfma_f32_16x16x32_bf16 v[96:99], v[198:201], v[222:225], v[96:99]
	v_mfma_f32_16x16x32_bf16 v[84:87], v[154:157], v[230:233], v[84:87]
	v_mfma_f32_16x16x32_bf16 v[68:71], v[198:201], v[230:233], v[68:71]
	s_setprio 0
	s_barrier
	s_add_i32 s82, s84, s67
	v_lshl_add_u64 v[158:159], s[40:41], 0, v[164:165]
	s_mov_b32 m0, s82
	ds_read_b128 v[202:205], v133 offset:16384
	ds_read_b128 v[206:209], v133 offset:17408
	ds_read_b128 v[210:213], v133 offset:18432
	ds_read_b128 v[214:217], v133 offset:19456
	ds_read_b128 v[218:221], v133 offset:20480
	ds_read_b128 v[222:225], v133 offset:21504
	ds_read_b128 v[226:229], v133 offset:22528
	ds_read_b128 v[230:233], v133 offset:23552
	global_load_lds_dwordx4 v[158:159], off
	s_add_i32 m0, s82, 0x2000
	s_add_u32 s82, s40, 0xb0000
	v_lshl_add_u64 v[176:177], s[40:41], 0, v[168:169]
	s_addc_u32 s83, s41, 0
	s_add_i32 s84, s85, s67
	global_load_lds_dwordx4 v[176:177], off
	v_lshl_add_u64 v[234:235], s[82:83], 0, v[164:165]
	s_mov_b32 m0, s84
	v_lshl_add_u64 v[236:237], s[42:43], 0, v[166:167]
	global_load_lds_dwordx4 v[234:235], off
	v_lshl_add_u64 v[234:235], s[82:83], 0, v[168:169]
	s_add_i32 m0, s84, 0x2000
	s_nop 0
	global_load_lds_dwordx4 v[234:235], off
	v_lshl_add_u64 v[234:235], s[42:43], 0, v[162:163]
	s_mov_b32 m0, s68
	s_nop 0
	global_load_lds_dwordx4 v[234:235], off
	s_mov_b32 m0, s69
	s_nop 0
	global_load_lds_dwordx4 v[236:237], off
	s_waitcnt vmcnt(8)
	s_waitcnt lgkmcnt(0)
	s_barrier
	s_setprio 1
	s_waitcnt lgkmcnt(0)
	v_mfma_f32_16x16x32_bf16 v[60:63], v[134:137], v[202:205], v[60:63]
	v_mfma_f32_16x16x32_bf16 v[56:59], v[142:145], v[202:205], v[56:59]
	v_mfma_f32_16x16x32_bf16 v[44:47], v[134:137], v[210:213], v[44:47]
	v_mfma_f32_16x16x32_bf16 v[40:43], v[142:145], v[210:213], v[40:43]
	v_mfma_f32_16x16x32_bf16 v[28:31], v[134:137], v[218:221], v[28:31]
	v_mfma_f32_16x16x32_bf16 v[24:27], v[142:145], v[218:221], v[24:27]
	v_mfma_f32_16x16x32_bf16 v[12:15], v[134:137], v[226:229], v[12:15]
	v_mfma_f32_16x16x32_bf16 v[8:11], v[142:145], v[226:229], v[8:11]
	v_mfma_f32_16x16x32_bf16 v[60:63], v[138:141], v[206:209], v[60:63]
	v_mfma_f32_16x16x32_bf16 v[56:59], v[146:149], v[206:209], v[56:59]
	v_mfma_f32_16x16x32_bf16 v[44:47], v[138:141], v[214:217], v[44:47]
	v_mfma_f32_16x16x32_bf16 v[40:43], v[146:149], v[214:217], v[40:43]
	v_mfma_f32_16x16x32_bf16 v[28:31], v[138:141], v[222:225], v[28:31]
	v_mfma_f32_16x16x32_bf16 v[24:27], v[146:149], v[222:225], v[24:27]
	v_mfma_f32_16x16x32_bf16 v[12:15], v[138:141], v[230:233], v[12:15]
	v_mfma_f32_16x16x32_bf16 v[8:11], v[146:149], v[230:233], v[8:11]
	s_setprio 0
	s_setprio 1
	v_mfma_f32_16x16x32_bf16 v[52:55], v[150:153], v[202:205], v[52:55]
	v_mfma_f32_16x16x32_bf16 v[48:51], v[194:197], v[202:205], v[48:51]
	v_mfma_f32_16x16x32_bf16 v[36:39], v[150:153], v[210:213], v[36:39]
	v_mfma_f32_16x16x32_bf16 v[32:35], v[194:197], v[210:213], v[32:35]
	v_mfma_f32_16x16x32_bf16 v[20:23], v[150:153], v[218:221], v[20:23]
	v_mfma_f32_16x16x32_bf16 v[16:19], v[194:197], v[218:221], v[16:19]
	v_mfma_f32_16x16x32_bf16 v[4:7], v[150:153], v[226:229], v[4:7]
	v_mfma_f32_16x16x32_bf16 v[0:3], v[194:197], v[226:229], v[0:3]
	v_mfma_f32_16x16x32_bf16 v[52:55], v[154:157], v[206:209], v[52:55]
	v_mfma_f32_16x16x32_bf16 v[48:51], v[198:201], v[206:209], v[48:51]
	v_mfma_f32_16x16x32_bf16 v[36:39], v[154:157], v[214:217], v[36:39]
	v_mfma_f32_16x16x32_bf16 v[32:35], v[198:201], v[214:217], v[32:35]
	v_mfma_f32_16x16x32_bf16 v[20:23], v[154:157], v[222:225], v[20:23]
	v_mfma_f32_16x16x32_bf16 v[16:19], v[198:201], v[222:225], v[16:19]
	v_mfma_f32_16x16x32_bf16 v[4:7], v[154:157], v[230:233], v[4:7]
	v_mfma_f32_16x16x32_bf16 v[0:3], v[198:201], v[230:233], v[0:3]
	s_setprio 0
	s_barrier
	s_add_i32 s82, 0, 0x18000
	s_add_i32 s83, 0, 0x1c000
	v_add_u32_e32 v146, s82, v132
	v_add_u32_e32 v160, s83, v132
	ds_read_b128 v[134:137], v146
	ds_read_b128 v[138:141], v146 offset:1024
	ds_read_b128 v[142:145], v146 offset:2048
	ds_read_b128 v[146:149], v146 offset:3072
	ds_read_b128 v[150:153], v160
	ds_read_b128 v[154:157], v160 offset:1024
	ds_read_b128 v[194:197], v160 offset:2048
	ds_read_b128 v[198:201], v160 offset:3072
	s_add_u32 s42, s42, 0xb0000
	s_addc_u32 s43, s43, 0
	s_mov_b32 m0, s71
	v_lshl_add_u64 v[238:239], s[42:43], 0, v[162:163]
	ds_read_b128 v[202:205], v133 offset:32768
	ds_read_b128 v[206:209], v133 offset:33792
	ds_read_b128 v[210:213], v133 offset:34816
	ds_read_b128 v[214:217], v133 offset:35840
	ds_read_b128 v[218:221], v133 offset:36864
	ds_read_b128 v[222:225], v133 offset:37888
	ds_read_b128 v[226:229], v133 offset:38912
	ds_read_b128 v[230:233], v133 offset:39936
	global_load_lds_dwordx4 v[238:239], off
	v_lshl_add_u64 v[238:239], s[42:43], 0, v[166:167]
	s_mov_b32 m0, s72
	s_nop 0
	global_load_lds_dwordx4 v[238:239], off
	s_waitcnt vmcnt(8)
	s_waitcnt lgkmcnt(0)
	s_barrier
	s_setprio 1
	s_waitcnt lgkmcnt(0)
	v_mfma_f32_16x16x32_bf16 v[80:83], v[134:137], v[202:205], v[80:83]
	v_mfma_f32_16x16x32_bf16 v[76:79], v[142:145], v[202:205], v[76:79]
	v_mfma_f32_16x16x32_bf16 v[124:127], v[134:137], v[210:213], v[124:127]
	v_mfma_f32_16x16x32_bf16 v[104:107], v[142:145], v[210:213], v[104:107]
	v_mfma_f32_16x16x32_bf16 v[116:119], v[134:137], v[218:221], v[116:119]
	v_mfma_f32_16x16x32_bf16 v[108:111], v[142:145], v[218:221], v[108:111]
	v_mfma_f32_16x16x32_bf16 v[120:123], v[134:137], v[226:229], v[120:123]
	v_mfma_f32_16x16x32_bf16 v[112:115], v[142:145], v[226:229], v[112:115]
	v_mfma_f32_16x16x32_bf16 v[80:83], v[138:141], v[206:209], v[80:83]
	v_mfma_f32_16x16x32_bf16 v[76:79], v[146:149], v[206:209], v[76:79]
	v_mfma_f32_16x16x32_bf16 v[124:127], v[138:141], v[214:217], v[124:127]
	v_mfma_f32_16x16x32_bf16 v[104:107], v[146:149], v[214:217], v[104:107]
	v_mfma_f32_16x16x32_bf16 v[116:119], v[138:141], v[222:225], v[116:119]
	v_mfma_f32_16x16x32_bf16 v[108:111], v[146:149], v[222:225], v[108:111]
	v_mfma_f32_16x16x32_bf16 v[120:123], v[138:141], v[230:233], v[120:123]
	v_mfma_f32_16x16x32_bf16 v[112:115], v[146:149], v[230:233], v[112:115]
	s_setprio 0
	s_setprio 1
	v_mfma_f32_16x16x32_bf16 v[72:75], v[150:153], v[202:205], v[72:75]
	v_mfma_f32_16x16x32_bf16 v[64:67], v[194:197], v[202:205], v[64:67]
	v_mfma_f32_16x16x32_bf16 v[92:95], v[150:153], v[210:213], v[92:95]
	v_mfma_f32_16x16x32_bf16 v[88:91], v[194:197], v[210:213], v[88:91]
	v_mfma_f32_16x16x32_bf16 v[100:103], v[150:153], v[218:221], v[100:103]
	v_mfma_f32_16x16x32_bf16 v[96:99], v[194:197], v[218:221], v[96:99]
	v_mfma_f32_16x16x32_bf16 v[84:87], v[150:153], v[226:229], v[84:87]
	v_mfma_f32_16x16x32_bf16 v[68:71], v[194:197], v[226:229], v[68:71]
	v_mfma_f32_16x16x32_bf16 v[72:75], v[154:157], v[206:209], v[72:75]
	v_mfma_f32_16x16x32_bf16 v[64:67], v[198:201], v[206:209], v[64:67]
	v_mfma_f32_16x16x32_bf16 v[92:95], v[154:157], v[214:217], v[92:95]
	v_mfma_f32_16x16x32_bf16 v[88:91], v[198:201], v[214:217], v[88:91]
	v_mfma_f32_16x16x32_bf16 v[100:103], v[154:157], v[222:225], v[100:103]
	v_mfma_f32_16x16x32_bf16 v[96:99], v[198:201], v[222:225], v[96:99]
	v_mfma_f32_16x16x32_bf16 v[84:87], v[154:157], v[230:233], v[84:87]
	v_mfma_f32_16x16x32_bf16 v[68:71], v[198:201], v[230:233], v[68:71]
	s_setprio 0
	s_barrier
	s_add_i32 s42, s82, s67
	v_lshl_add_u64 v[158:159], v[158:159], 0, s[22:23]
	s_mov_b32 m0, s42
	ds_read_b128 v[202:205], v133 offset:49152
	ds_read_b128 v[206:209], v133 offset:50176
	ds_read_b128 v[210:213], v133 offset:51200
	ds_read_b128 v[214:217], v133 offset:52224
	ds_read_b128 v[218:221], v133 offset:53248
	ds_read_b128 v[222:225], v133 offset:54272
	ds_read_b128 v[226:229], v133 offset:55296
	ds_read_b128 v[230:233], v133 offset:56320
	global_load_lds_dwordx4 v[158:159], off
	s_add_i32 m0, s42, 0x2000
	s_add_u32 s40, s40, 0xb0080
	v_lshl_add_u64 v[158:159], v[176:177], 0, s[22:23]
	s_addc_u32 s41, s41, 0
	s_add_i32 s42, s83, s67
	global_load_lds_dwordx4 v[158:159], off
	v_lshl_add_u64 v[158:159], s[40:41], 0, v[164:165]
	s_mov_b32 m0, s42
	s_nop 0
	global_load_lds_dwordx4 v[158:159], off
	v_lshl_add_u64 v[158:159], s[40:41], 0, v[168:169]
	s_add_i32 m0, s42, 0x2000
	s_nop 0
	global_load_lds_dwordx4 v[158:159], off
	v_lshl_add_u64 v[158:159], v[234:235], 0, s[22:23]
	s_mov_b32 m0, s73
	s_nop 0
	global_load_lds_dwordx4 v[158:159], off
	v_lshl_add_u64 v[158:159], v[236:237], 0, s[22:23]
	s_mov_b32 m0, s74
	s_nop 0
	global_load_lds_dwordx4 v[158:159], off
	s_waitcnt vmcnt(8)
	s_waitcnt lgkmcnt(0)
	s_barrier
	s_setprio 1
	s_waitcnt lgkmcnt(0)
	v_mfma_f32_16x16x32_bf16 v[60:63], v[134:137], v[202:205], v[60:63]
	v_mfma_f32_16x16x32_bf16 v[56:59], v[142:145], v[202:205], v[56:59]
	v_mfma_f32_16x16x32_bf16 v[44:47], v[134:137], v[210:213], v[44:47]
	v_mfma_f32_16x16x32_bf16 v[40:43], v[142:145], v[210:213], v[40:43]
	v_mfma_f32_16x16x32_bf16 v[28:31], v[134:137], v[218:221], v[28:31]
	v_mfma_f32_16x16x32_bf16 v[24:27], v[142:145], v[218:221], v[24:27]
	v_mfma_f32_16x16x32_bf16 v[12:15], v[134:137], v[226:229], v[12:15]
	v_mfma_f32_16x16x32_bf16 v[8:11], v[142:145], v[226:229], v[8:11]
	v_mfma_f32_16x16x32_bf16 v[60:63], v[138:141], v[206:209], v[60:63]
	v_mfma_f32_16x16x32_bf16 v[56:59], v[146:149], v[206:209], v[56:59]
	v_mfma_f32_16x16x32_bf16 v[44:47], v[138:141], v[214:217], v[44:47]
	v_mfma_f32_16x16x32_bf16 v[40:43], v[146:149], v[214:217], v[40:43]
	v_mfma_f32_16x16x32_bf16 v[28:31], v[138:141], v[222:225], v[28:31]
	v_mfma_f32_16x16x32_bf16 v[24:27], v[146:149], v[222:225], v[24:27]
	v_mfma_f32_16x16x32_bf16 v[12:15], v[138:141], v[230:233], v[12:15]
	v_mfma_f32_16x16x32_bf16 v[8:11], v[146:149], v[230:233], v[8:11]
	s_setprio 0
	s_setprio 1
	v_mfma_f32_16x16x32_bf16 v[52:55], v[150:153], v[202:205], v[52:55]
	v_mfma_f32_16x16x32_bf16 v[48:51], v[194:197], v[202:205], v[48:51]
	v_mfma_f32_16x16x32_bf16 v[36:39], v[150:153], v[210:213], v[36:39]
	v_mfma_f32_16x16x32_bf16 v[32:35], v[194:197], v[210:213], v[32:35]
	v_mfma_f32_16x16x32_bf16 v[20:23], v[150:153], v[218:221], v[20:23]
	v_mfma_f32_16x16x32_bf16 v[16:19], v[194:197], v[218:221], v[16:19]
	v_mfma_f32_16x16x32_bf16 v[4:7], v[150:153], v[226:229], v[4:7]
	v_mfma_f32_16x16x32_bf16 v[0:3], v[194:197], v[226:229], v[0:3]
	v_mfma_f32_16x16x32_bf16 v[52:55], v[154:157], v[206:209], v[52:55]
	v_mfma_f32_16x16x32_bf16 v[48:51], v[198:201], v[206:209], v[48:51]
	v_mfma_f32_16x16x32_bf16 v[36:39], v[154:157], v[214:217], v[36:39]
	v_mfma_f32_16x16x32_bf16 v[32:35], v[198:201], v[214:217], v[32:35]
	v_mfma_f32_16x16x32_bf16 v[20:23], v[154:157], v[222:225], v[20:23]
	v_mfma_f32_16x16x32_bf16 v[16:19], v[198:201], v[222:225], v[16:19]
	v_mfma_f32_16x16x32_bf16 v[4:7], v[154:157], v[230:233], v[4:7]
	v_mfma_f32_16x16x32_bf16 v[0:3], v[198:201], v[230:233], v[0:3]
	s_setprio 0
	s_barrier
	s_add_i32 s81, s81, 2
	s_add_u32 s38, s38, 0x100
	s_addc_u32 s39, s39, 0
	s_cmp_gt_u32 s81, 41
	s_cbranch_scc0 .LBB0_1277
	s_add_u32 s38, s79, 0xffffff00
	s_addc_u32 s39, s80, -1
	s_and_b64 vcc, exec, s[8:9]
	s_cbranch_vccnz .LBB0_1280
	v_mov_b32_e32 v0, 0
	s_mov_b32 s26, s76
	s_mov_b32 s58, s77
	s_mov_b64 s[28:29], s[36:37]
	s_mov_b32 s75, s78
	v_mov_b32_e32 v1, 0
	v_mov_b64_e32 v[2:3], 0
	v_mov_b64_e32 v[4:5], 0
	v_mov_b64_e32 v[6:7], 0
	v_mov_b64_e32 v[16:17], 0
	v_mov_b64_e32 v[18:19], 0
	v_mov_b64_e32 v[20:21], 0
	v_mov_b64_e32 v[22:23], 0
	v_mov_b64_e32 v[32:33], 0
	v_mov_b64_e32 v[34:35], 0
	v_mov_b64_e32 v[36:37], 0
	v_mov_b64_e32 v[38:39], 0
	v_mov_b64_e32 v[48:49], 0
	v_mov_b64_e32 v[50:51], 0
	v_mov_b64_e32 v[52:53], 0
	v_mov_b64_e32 v[54:55], 0
	v_mov_b64_e32 v[8:9], 0
	v_mov_b64_e32 v[10:11], 0
	v_mov_b64_e32 v[12:13], 0
	v_mov_b64_e32 v[14:15], 0
	v_mov_b64_e32 v[24:25], 0
	v_mov_b64_e32 v[26:27], 0
	v_mov_b64_e32 v[28:29], 0
	v_mov_b64_e32 v[30:31], 0
	v_mov_b64_e32 v[40:41], 0
	v_mov_b64_e32 v[42:43], 0
	v_mov_b64_e32 v[44:45], 0
	v_mov_b64_e32 v[46:47], 0
	v_mov_b64_e32 v[56:57], 0
	v_mov_b64_e32 v[58:59], 0
	v_mov_b64_e32 v[60:61], 0
	v_mov_b64_e32 v[62:63], 0
	v_mov_b64_e32 v[68:69], 0
	v_mov_b64_e32 v[70:71], 0
	v_mov_b64_e32 v[84:85], 0
	v_mov_b64_e32 v[86:87], 0
	v_mov_b64_e32 v[96:97], 0
	v_mov_b64_e32 v[98:99], 0
	v_mov_b64_e32 v[100:101], 0
	v_mov_b64_e32 v[102:103], 0
	v_mov_b64_e32 v[88:89], 0
	v_mov_b64_e32 v[90:91], 0
	v_mov_b64_e32 v[92:93], 0
	v_mov_b64_e32 v[94:95], 0
	v_mov_b64_e32 v[64:65], 0
	v_mov_b64_e32 v[66:67], 0
	v_mov_b64_e32 v[72:73], 0
	v_mov_b64_e32 v[74:75], 0
	v_mov_b64_e32 v[112:113], 0
	v_mov_b64_e32 v[114:115], 0
	v_mov_b64_e32 v[120:121], 0
	v_mov_b64_e32 v[122:123], 0
	v_mov_b64_e32 v[108:109], 0
	v_mov_b64_e32 v[110:111], 0
	v_mov_b64_e32 v[116:117], 0
	v_mov_b64_e32 v[118:119], 0
	v_mov_b64_e32 v[104:105], 0
	v_mov_b64_e32 v[106:107], 0
	v_mov_b64_e32 v[124:125], 0
	v_mov_b64_e32 v[126:127], 0
	v_mov_b64_e32 v[76:77], 0
	v_mov_b64_e32 v[78:79], 0
	v_mov_b64_e32 v[80:81], 0
	v_mov_b64_e32 v[82:83], 0
	s_andn2_b64 vcc, exec, s[30:31]
	s_cbranch_vccnz .LBB0_1281
	s_branch .LBB0_1282
